# even scans: stage2 of the two chunks of an interval interleaved instruction-by-instruction (second chunk's temporaries renamed to free registers, LDS waits recomputed)
# speedup vs baseline: 1.0011x; 1.0007x over previous
; template <int MODE>
; __device__ void scan_unit(int swave, const Params& p, int j, int b, int h, int dir, char* shm) {
;     ...
;   auto compute = [&](const char* buf, bf16_t* obuf) {
;     const bf16_t* qin = (const bf16_t*)buf; const bf16_t* ktil = (const bf16_t*)(buf + OFF_KT); const bf16_t* koutT = (const bf16_t*)(buf + OFF_KO);
;     const bf16_t* vT = (const bf16_t*)(buf + OFF_VT); const float* dec = (const float*)(buf + OFF_DEC);
;     bf16x8 Asc = {0, 0, 0, 0, 0, 0, 0, 0};
;     if (KS == 1 || wk == 0) {
;       f32x4 sc = {0.f, 0.f, 0.f, 0.f};
; #pragma unroll
;       for (int m = 0; m < DK / 32; ++m) {
;         const bf16x8 a = *(const bf16x8*)(ktil + r * QS + m * 32 + q4 * 8);
;         const bf16x8 bb = *(const bf16x8*)(qin + r * QS + m * 32 + q4 * 8);
;         sc = __builtin_amdgcn_mfma_f32_16x16x32_bf16(a, bb, sc, 0, 0, 0);
;       }
;       {
;         const unsigned p01 = pk2(q4 * 4 + 0 > r ? 0.f : sc[0], q4 * 4 + 1 > r ? 0.f : sc[1]);
;         const unsigned p23 = pk2(q4 * 4 + 2 > r ? 0.f : sc[2], q4 * 4 + 3 > r ? 0.f : sc[3]);
;         Asc[0] = (short)(p01 & 0xffff); Asc[1] = (short)(p01 >> 16); Asc[2] = (short)(p23 & 0xffff); Asc[3] = (short)(p23 >> 16);
;       }
;     }
;     bf16x8 Bv[NVT];
; #pragma unroll
;     for (int t = 0; t < NVT; ++t) {
;       const uint2 vv = *(const uint2*)(vT + ((vt0 + t) * 16 + r) * VS + q4 * 4);
;       Bv[t] = (bf16x8){(short)(vv.x & 0xffff), (short)(vv.x >> 16), (short)(vv.y & 0xffff), (short)(vv.y >> 16), 0, 0, 0, 0};
;     }
;     bf16x8 Aq[2];
; #pragma unroll
;     for (int m = 0; m < 2; ++m) {
;       const uint2 lo = *(const uint2*)(qin + r * QS + slab + (2 * m) * 16 + q4 * 4);
;       const uint2 hi = *(const uint2*)(qin + r * QS + slab + (2 * m + 1) * 16 + q4 * 4);
;       Aq[m] = (bf16x8){(short)(lo.x & 0xffff), (short)(lo.x >> 16), (short)(lo.y & 0xffff), (short)(lo.y >> 16),
;                        (short)(hi.x & 0xffff), (short)(hi.x >> 16), (short)(hi.y & 0xffff), (short)(hi.y >> 16)};
;     }
;     f32x4 o[NVT];
; #pragma unroll
;     for (int t = 0; t < NVT; ++t) {
;       o[t] = (f32x4){0.f, 0.f, 0.f, 0.f};
;       if (KS == 1 || wk == 0) o[t] = __builtin_amdgcn_mfma_f32_16x16x32_bf16(Asc, Bv[t], o[t], 0, 0, 0);
;     }
; #pragma unroll
;     for (int m = 0; m < 2; ++m)
; #pragma unroll
;       for (int t = 0; t < NVT; ++t) {
;         const f32x4 s0 = S[2 * m][t], s1 = S[2 * m + 1][t];
.LBB0_646:
	ds_write_b16 v42, v32 offset:18688
	ds_write_b16_d16_hi v42, v32 offset:18728
	ds_write_b16 v42, v33 offset:18768
	ds_write_b16_d16_hi v42, v33 offset:18808
	ds_read_b128 v[32:35], v46 offset:26368
	ds_read_b128 v[64:67], v46 offset:24064
	ds_read_b128 v[68:71], v46 offset:26432
	ds_read_b128 v[72:75], v46 offset:24128
	v_add_u32_e32 v0, 0x5800, v53
	v_add_u32_e32 v56, 0x8800, v53
	s_waitcnt lgkmcnt(2)
	v_mfma_f32_16x16x32_bf16 v[32:35], v[32:35], v[64:67], 0
	ds_read_b64 v[64:65], v47 offset:30720
	ds_read2_b64 v[76:79], v0 offset0:192 offset1:196
	ds_read2_b64 v[80:83], v0 offset0:200 offset1:204
	v_mov_b32_e32 v66, v3
	v_mov_b32_e32 v67, v3
	s_waitcnt lgkmcnt(3)
	v_mfma_f32_16x16x32_bf16 v[32:35], v[68:71], v[72:75], v[32:35]
	s_waitcnt lgkmcnt(1)
	v_bfi_b32 v78, s30, v78, v78
	s_waitcnt lgkmcnt(0)
	v_bfi_b32 v82, s30, v82, v82
	v_cvt_pk_bf16_f32 v68, v8, v9
	v_cvt_pk_bf16_f32 v69, v10, v11
	v_cvt_pk_bf16_f32 v70, v12, v13
	s_nop 0
	v_cndmask_b32_e64 v0, v32, 0, s[6:7]
	v_cndmask_b32_e64 v1, 0, v33, s[8:9]
	v_cndmask_b32_e64 v2, v34, 0, s[10:11]
	v_cndmask_b32_e64 v32, v35, 0, s[12:13]
	v_cvt_pk_bf16_f32 v0, v0, v1
	v_cvt_pk_bf16_f32 v1, v2, v32
	v_mov_b32_e32 v2, v3
	v_cvt_pk_bf16_f32 v71, v14, v15
	s_add_i32 s35, s35, 2
	v_mfma_f32_16x16x32_bf16 v[32:35], v[0:3], v[64:67], 0
	s_and_b64 vcc, exec, s[74:75]
	v_mfma_f32_16x16x32_bf16 v[32:35], v[76:79], v[68:71], v[32:35]
	v_cvt_pk_bf16_f32 v68, v16, v17
	v_cvt_pk_bf16_f32 v69, v18, v19
	v_cvt_pk_bf16_f32 v70, v4, v5
	v_cvt_pk_bf16_f32 v71, v6, v7
	s_nop 1
	v_mfma_f32_16x16x32_bf16 v[32:35], v[80:83], v[68:71], v[32:35]
	s_nop 7
	v_cvt_pk_bf16_f32 v0, v32, s0
	ds_write_b16 v48, v0 offset:56576
	v_cvt_pk_bf16_f32 v0, v33, s0
	ds_write_b16 v48, v0 offset:56840
	v_cvt_pk_bf16_f32 v0, v34, s0
	ds_write_b16 v48, v0 offset:57104
	v_cvt_pk_bf16_f32 v0, v35, s0
	ds_write_b16 v48, v0 offset:57368
	ds_read2st64_b64 v[32:35], v49 offset0:56 offset1:57
	ds_read2st64_b64 v[68:71], v49 offset0:58 offset1:59
	ds_read_b128 v[72:75], v50 offset:35840
	ds_read_b128 v[76:79], v50 offset:35904
	s_waitcnt lgkmcnt(3)
	s_waitcnt lgkmcnt(1)
	v_pk_mul_f32 v[10:11], v[10:11], v[74:75]
	v_pk_mul_f32 v[8:9], v[8:9], v[72:73]
	s_waitcnt lgkmcnt(0)
	v_pk_mul_f32 v[14:15], v[14:15], v[78:79]
	v_pk_mul_f32 v[12:13], v[12:13], v[76:77]
	v_mfma_f32_16x16x16_bf16 v[8:11], v[32:33], v[64:65], v[8:11]
	v_mov_b32_e32 v0, v34
	v_mov_b32_e32 v1, v35
	ds_read_b128 v[32:35], v50 offset:35968
	ds_read_b128 v[72:75], v50 offset:36032
	v_mfma_f32_16x16x16_bf16 v[12:15], v[0:1], v[64:65], v[12:15]
	s_waitcnt lgkmcnt(1)
	v_pk_mul_f32 v[18:19], v[18:19], v[34:35]
	v_pk_mul_f32 v[16:17], v[16:17], v[32:33]
	v_cvt_pk_bf16_f32 v76, v8, v9
	v_cvt_pk_bf16_f32 v77, v10, v11
	v_mfma_f32_16x16x16_bf16 v[32:35], v[68:69], v[64:65], v[16:19]
	s_nop 1
	v_cvt_pk_bf16_f32 v78, v12, v13
	ds_read_b128 v[16:19], v46 offset:38400
	s_waitcnt lgkmcnt(1)
	v_pk_mul_f32 v[6:7], v[6:7], v[74:75]
	v_pk_mul_f32 v[4:5], v[4:5], v[72:73]
	v_cvt_pk_bf16_f32 v79, v14, v15
	s_nop 0
	v_mfma_f32_16x16x16_bf16 v[4:7], v[70:71], v[64:65], v[4:7]
	ds_read_b128 v[64:67], v46 offset:38464
	ds_read_b128 v[68:71], v46 offset:36096
	ds_read_b128 v[72:75], v46 offset:36160
	s_waitcnt lgkmcnt(1)
	v_mfma_f32_16x16x32_bf16 v[16:19], v[16:19], v[68:71], 0
	v_mov_b32_e32 v70, v3
	v_mov_b32_e32 v71, v3
	s_waitcnt lgkmcnt(0)
	v_mfma_f32_16x16x32_bf16 v[16:19], v[64:67], v[72:75], v[16:19]
	s_nop 7
	v_cndmask_b32_e64 v0, v16, 0, s[6:7]
	v_cndmask_b32_e64 v1, 0, v17, s[8:9]
	v_cvt_pk_bf16_f32 v0, v0, v1
	v_cndmask_b32_e64 v1, v18, 0, s[10:11]
	v_cndmask_b32_e64 v2, v19, 0, s[12:13]
	ds_read2_b64 v[16:19], v56 offset0:160 offset1:164
	ds_read2_b64 v[64:67], v56 offset0:168 offset1:172
	v_cvt_pk_bf16_f32 v1, v1, v2
	ds_read_b64 v[68:69], v47 offset:42752
	v_mov_b32_e32 v2, v3
	s_waitcnt lgkmcnt(2)
	v_bfi_b32 v18, s30, v18, v18
	s_waitcnt lgkmcnt(1)
	v_bfi_b32 v66, s30, v66, v66
	s_waitcnt lgkmcnt(0)
	v_mfma_f32_16x16x32_bf16 v[72:75], v[0:3], v[68:71], 0
	v_mfma_f32_16x16x32_bf16 v[16:19], v[16:19], v[76:79], v[72:75]
	s_nop 6
	v_cvt_pk_bf16_f32 v72, v32, v33
	v_cvt_pk_bf16_f32 v73, v34, v35
	v_cvt_pk_bf16_f32 v74, v4, v5
	v_cvt_pk_bf16_f32 v75, v6, v7
	s_nop 1
	v_mfma_f32_16x16x32_bf16 v[16:19], v[64:67], v[72:75], v[16:19]
	s_nop 7
	v_cvt_pk_bf16_f32 v0, v16, s0
	ds_write_b16 v48, v0 offset:60800
	v_cvt_pk_bf16_f32 v0, v17, s0
	ds_write_b16 v48, v0 offset:61064
	v_cvt_pk_bf16_f32 v0, v18, s0
	ds_write_b16 v48, v0 offset:61328
	v_cvt_pk_bf16_f32 v0, v19, s0
	ds_write_b16 v48, v0 offset:61592
	ds_read2st64_b64 v[64:67], v62 offset0:79 offset1:80
	ds_read2st64_b64 v[60:63], v62 offset0:81 offset1:82
	ds_read_b128 v[16:19], v50 offset:47872
	ds_read_b128 v[72:75], v50 offset:47936
	s_waitcnt lgkmcnt(3)
	s_waitcnt lgkmcnt(1)
	v_pk_mul_f32 v[10:11], v[10:11], v[18:19]
	v_pk_mul_f32 v[8:9], v[8:9], v[16:17]
	s_nop 1
	v_mfma_f32_16x16x16_bf16 v[16:19], v[64:65], v[68:69], v[8:11]
	v_mov_b32_e32 v0, v66
	v_mov_b32_e32 v1, v67
	ds_read_b128 v[64:67], v50 offset:48064
	s_waitcnt lgkmcnt(1)
	v_pk_mul_f32 v[10:11], v[14:15], v[74:75]
	v_pk_mul_f32 v[8:9], v[12:13], v[72:73]
	s_waitcnt lgkmcnt(0)
	v_pk_mul_f32 v[6:7], v[6:7], v[66:67]
	v_mfma_f32_16x16x16_bf16 v[12:15], v[0:1], v[68:69], v[8:11]
	v_pk_mul_f32 v[4:5], v[4:5], v[64:65]
	ds_read_b128 v[8:11], v50 offset:48000
	s_waitcnt lgkmcnt(0)
	s_barrier
	s_waitcnt lgkmcnt(0)
	v_pk_mul_f32 v[10:11], v[34:35], v[10:11]
	v_pk_mul_f32 v[8:9], v[32:33], v[8:9]
	s_nop 1
	v_mfma_f32_16x16x16_bf16 v[8:11], v[60:61], v[68:69], v[8:11]
	v_mov_b32_e32 v0, v62
	v_mov_b32_e32 v1, v63
	s_nop 1
	v_mfma_f32_16x16x16_bf16 v[4:7], v[62:63], v[68:69], v[4:7]
	s_cbranch_vccnz .LBB0_665

; __device__ __forceinline__ bf16_t f2bf(float f) { return (bf16_t)(pk2(f, 0.f) & 0xffffu); }
; template <int MODE>
; __device__ void scan_unit(int swave, const Params& p, int j, int b, int h, int dir, char* shm) {
;     ...
;   auto stage2 = [&](const Raw& R, char* buf, int c) {
;     bf16_t* qin = (bf16_t*)buf; bf16_t* ktil = (bf16_t*)(buf + OFF_KT); bf16_t* koutT = (bf16_t*)(buf + OFF_KO);
;     bf16_t* vT = (bf16_t*)(buf + OFF_VT); float* dec = (float*)(buf + OFF_DEC);
;     if (MODE != 2) {
;       float g0, g1;
;       if (MODE == 0) {
;         float z0 = bav0, z1 = bav1;
;         const unsigned lw[8] = {R.lr0.x, R.lr0.y, R.lr0.z, R.lr0.w, R.lr1.x, R.lr1.y, R.lr1.z, R.lr1.w};
; #pragma unroll
;         for (int e = 0; e < 8; ++e) {
;           const float a0 = lo_bf(lw[e]), a1 = hi_bf(lw[e]);
;           z0 += a0 * wa2r[4 * e] + a1 * wa2r[4 * e + 2];
;           z1 += a0 * wa2r[4 * e + 1] + a1 * wa2r[4 * e + 3];
;         }
;         g0 = (fminf(z0, 0.f) - __logf(1.f + __expf(-fabsf(z0)))) * (1.f / 16.f);
;         g1 = (fminf(z1, 0.f) - __logf(1.f + __expf(-fabsf(z1)))) * (1.f / 16.f);
;       } else {
;         const float f0 = lbv0 + (1.f - lbv0) * sigmoidf_(lo_bf(R.k)), f1 = lbv1 + (1.f - lbv1) * sigmoidf_(hi_bf(R.k));
;         g0 = __logf(fmaxf(f0, 1e-20f)); g1 = __logf(fmaxf(f1, 1e-20f));
;       }
;       float s0, s1;
;       const float cum0 = row_scan(g0, s0), cum1 = row_scan(g1, s1);
;       float q0, q1, k0, k1;
;       if (MODE == 0) { q0 = lo_bf(R.q); q1 = hi_bf(R.q); k0 = lo_bf(R.k) * 0.125f; k1 = hi_bf(R.k) * 0.125f; }
;       else { q0 = siluf_(lo_bf(R.q)); q1 = siluf_(hi_bf(R.q)); k0 = (1.f - lbv0) * sigmoidf_(-lo_bf(R.k)); k1 = (1.f - lbv1) * sigmoidf_(-hi_bf(R.k)); }
;       *(unsigned*)(qin + ti * QS + dp) = pk2(q0 * __expf(cum0), q1 * __expf(cum1));
;       *(unsigned*)(ktil + ti * QS + dp) = pk2(k0 * __expf(-cum0), k1 * __expf(-cum1));
;       koutT[dp * 16 + ti] = f2bf(k0 * __expf(s0 - cum0));
;       koutT[(dp + 1) * 16 + ti] = f2bf(k1 * __expf(s1 - cum1));
;       if (ti == 0) *(float2*)(dec + dp) = make_float2(__expf(s0), __expf(s1));
;       const unsigned v0 = R.v.x, v1 = R.v.y; const int c4 = vg * 4;
;       vT[(c4 + 0) * VS + ti] = (bf16_t)(v0 & 0xffff); vT[(c4 + 1) * VS + ti] = (bf16_t)(v0 >> 16);
;       vT[(c4 + 2) * VS + ti] = (bf16_t)(v1 & 0xffff); vT[(c4 + 3) * VS + ti] = (bf16_t)(v1 >> 16);
.Llw_join_647a:
	v_lshlrev_b32_e32 v172, 16, v55
	v_lshlrev_b32_e32 v2, 16, v59
	v_mul_f32_e32 v170, 0xbfb8aa3b, v172
	v_mul_f32_e32 v0, 0xbfb8aa3b, v2
	v_exp_f32_e32 v170, v170
	v_exp_f32_e32 v0, v0
	v_and_b32_e32 v177, 0xffff0000, v55
	v_and_b32_e32 v59, 0xffff0000, v59
	v_mul_f32_e32 v171, 0xbfb8aa3b, v177
	v_mul_f32_e32 v1, 0xbfb8aa3b, v59
	v_exp_f32_e32 v171, v171
	v_exp_f32_e32 v1, v1
	v_add_f32_e32 v170, 1.0, v170
	v_add_f32_e32 v0, 1.0, v0
	v_rcp_f32_e32 v170, v170
	v_rcp_f32_e32 v0, v0
	ds_write_b16 v42, v30 offset:30720
	v_mul_f32_e32 v2, 0x3fb8aa3b, v2
	ds_write_b16_d16_hi v42, v30 offset:30760
	v_add_f32_e32 v1, 1.0, v1
	v_add_f32_e32 v171, 1.0, v171
	v_rcp_f32_e32 v1, v1
	v_rcp_f32_e32 v171, v171
	v_fma_f32 v0, v24, v0, v20
	v_fma_f32 v170, v24, v170, v20
	v_max_f32_e32 v170, 0x1e3ce508, v170
	v_max_f32_e32 v0, 0x1e3ce508, v0
	v_cmp_gt_f32_e64 s[36:37], s26, v170
	v_cmp_gt_f32_e32 vcc, s26, v0
	v_fma_f32 v171, v25, v171, v21
	v_fma_f32 v1, v25, v1, v21
	v_max_f32_e32 v171, 0x1e3ce508, v171
	v_max_f32_e32 v1, 0x1e3ce508, v1
	v_cndmask_b32_e64 v174, 0, 32, s[36:37]
	v_cndmask_b32_e64 v62, 0, 32, vcc
	v_ldexp_f32 v170, v170, v174
	v_ldexp_f32 v0, v0, v62
	v_log_f32_e32 v170, v170
	v_log_f32_e32 v0, v0
	v_cmp_gt_f32_e64 s[38:39], s26, v171
	v_cmp_gt_f32_e64 s[16:17], s26, v1
	ds_write_b16 v42, v31 offset:30800
	v_exp_f32_e32 v2, v2
	ds_write_b16_d16_hi v42, v31 offset:30840
	v_mul_f32_e32 v59, 0x3fb8aa3b, v59
	v_cndmask_b32_e64 v175, 0, 32, s[38:39]
	v_cndmask_b32_e64 v62, 0, 32, s[16:17]
	v_mul_f32_e32 v174, 0x3f317217, v170
	v_mul_f32_e32 v63, 0x3f317217, v0
	v_ldexp_f32 v171, v171, v175
	v_fma_f32 v174, v170, s31, -v174
	v_ldexp_f32 v1, v1, v62
	v_log_f32_e32 v171, v171
	v_fma_f32 v63, v0, s31, -v63
	v_fmac_f32_e32 v174, 0x3377d1cf, v170
	v_log_f32_e32 v1, v1
	v_fmac_f32_e32 v174, 0x3f317217, v170
	v_fmac_f32_e32 v63, 0x3377d1cf, v0
	v_cmp_lt_f32_e64 s[40:41], |v170|, s27
	v_fmac_f32_e32 v63, 0x3f317217, v0
	v_mul_f32_e32 v172, 0x3fb8aa3b, v172
	v_cmp_lt_f32_e64 s[18:19], |v0|, s27
	v_exp_f32_e32 v172, v172
	v_cndmask_b32_e32 v62, 0, v157, vcc
	v_cndmask_b32_e64 v170, v170, v174, s[40:41]
	v_exp_f32_e32 v59, v59
	v_cndmask_b32_e64 v174, 0, v157, s[36:37]
	v_cndmask_b32_e64 v0, v0, v63, s[18:19]
	v_sub_f32_e32 v170, v170, v174
	v_sub_f32_e32 v0, v0, v62
	v_mul_f32_e32 v174, 0x3f317217, v171
	v_mul_f32_e32 v62, 0x3f317217, v1
	v_mul_f32_e32 v175, 0x3fb8aa3b, v177
	v_fma_f32 v62, v1, s31, -v62
	v_fma_f32 v174, v171, s31, -v174
	v_exp_f32_e32 v177, v175
	v_fmac_f32_e32 v62, 0x3377d1cf, v1
	v_fmac_f32_e32 v174, 0x3377d1cf, v171
	v_fmac_f32_e32 v62, 0x3f317217, v1
	v_fmac_f32_e32 v174, 0x3f317217, v171
	v_cmp_lt_f32_e64 vcc, |v1|, s27
	v_cmp_lt_f32_e64 s[36:37], |v171|, s27
	v_add_f32_e32 v2, 1.0, v2
	v_add_f32_e32 v172, 1.0, v172
	v_rcp_f32_e32 v64, v2
	v_and_b32_e32 v175, 0xffff0000, v54
	v_cndmask_b32_e32 v1, v1, v62, vcc
	v_cndmask_b32_e64 v171, v171, v174, s[36:37]
	v_cndmask_b32_e64 v62, 0, v157, s[16:17]
	v_cndmask_b32_e64 v174, 0, v157, s[38:39]
	v_sub_f32_e32 v1, v1, v62
	v_sub_f32_e32 v171, v171, v174
	v_lshlrev_b32_e32 v62, 16, v57
	v_lshlrev_b32_e32 v174, 16, v54
	v_add_f32_e32 v2, 1.0, v59
	v_rcp_f32_e32 v176, v172
	v_and_b32_e32 v63, 0xffff0000, v57
	v_add_f32_e32 v172, 1.0, v177
	v_rcp_f32_e32 v177, v172
	v_rcp_f32_e32 v65, v2
	v_mul_f32_e32 v172, 0xbfb8aa3b, v174
	v_mul_f32_e32 v2, 0xbfb8aa3b, v62
	v_exp_f32_e32 v172, v172
	v_exp_f32_e32 v2, v2
	v_mul_f32_e32 v182, 0xbfb8aa3b, v175
	v_mul_f32_e32 v57, 0xbfb8aa3b, v63
	v_exp_f32_e32 v183, v182
	v_exp_f32_e32 v57, v57
	v_add_f32_dpp v170, v170, v170 row_shr:1 row_mask:0xf bank_mask:0xf bound_ctrl:1
	v_add_f32_dpp v0, v0, v0 row_shr:1 row_mask:0xf bank_mask:0xf bound_ctrl:1
	v_add_f32_dpp v171, v171, v171 row_shr:1 row_mask:0xf bank_mask:0xf bound_ctrl:1
	v_add_f32_dpp v1, v1, v1 row_shr:1 row_mask:0xf bank_mask:0xf bound_ctrl:1
	v_add_f32_e32 v172, 1.0, v172
	v_add_f32_e32 v2, 1.0, v2
	v_add_f32_dpp v170, v170, v170 row_shr:2 row_mask:0xf bank_mask:0xf bound_ctrl:1
	v_add_f32_dpp v0, v0, v0 row_shr:2 row_mask:0xf bank_mask:0xf bound_ctrl:1
	v_add_f32_dpp v171, v171, v171 row_shr:2 row_mask:0xf bank_mask:0xf bound_ctrl:1
	v_add_f32_dpp v1, v1, v1 row_shr:2 row_mask:0xf bank_mask:0xf bound_ctrl:1
	v_rcp_f32_e32 v182, v172
	v_rcp_f32_e32 v66, v2
	v_add_f32_e32 v172, 1.0, v183
	v_add_f32_e32 v2, 1.0, v57
	v_add_f32_dpp v170, v170, v170 row_shr:4 row_mask:0xf bank_mask:0xf bound_ctrl:1
	v_add_f32_dpp v171, v171, v171 row_shr:4 row_mask:0xf bank_mask:0xf bound_ctrl:1
	v_add_f32_dpp v0, v0, v0 row_shr:4 row_mask:0xf bank_mask:0xf bound_ctrl:1
	v_rcp_f32_e32 v183, v172
	v_add_f32_dpp v1, v1, v1 row_shr:4 row_mask:0xf bank_mask:0xf bound_ctrl:1
	v_add_f32_dpp v179, v170, v170 row_shr:8 row_mask:0xf bank_mask:0xf bound_ctrl:1
	v_rcp_f32_e32 v67, v2
	v_add_f32_dpp v181, v171, v171 row_shr:8 row_mask:0xf bank_mask:0xf bound_ctrl:1
	v_add_f32_dpp v70, v0, v0 row_shr:8 row_mask:0xf bank_mask:0xf bound_ctrl:1
	v_mul_f32_e32 v184, 0x3fb8aa3b, v179
	v_add_f32_dpp v71, v1, v1 row_shr:8 row_mask:0xf bank_mask:0xf bound_ctrl:1
	v_mul_f32_e32 v172, 0x3fb8aa3b, v181
	v_mul_f32_e32 v59, 0x3fb8aa3b, v70
	v_exp_f32_e32 v184, v184
	v_mul_f32_e32 v2, 0x3fb8aa3b, v71
	v_exp_f32_e32 v185, v172
	v_exp_f32_e32 v68, v59
	v_mul_f32_e32 v172, 0xbfb8aa3b, v179
	v_exp_f32_e32 v69, v2
	v_pk_mul_f32 v[174:175], v[182:183], v[174:175]
	v_mul_f32_e32 v2, 0xbfb8aa3b, v70
	v_exp_f32_e32 v182, v172
	v_pk_mul_f32 v[62:63], v[66:67], v[62:63]
	v_mul_f32_e32 v172, 0xbfb8aa3b, v181
	v_exp_f32_e32 v66, v2
	v_exp_f32_e32 v183, v172
	ds_bpermute_b32 v170, v38, v179
	v_mul_f32_e32 v2, 0xbfb8aa3b, v71
	v_pk_mul_f32 v[174:175], v[174:175], v[184:185]
	v_exp_f32_e32 v67, v2
	ds_bpermute_b32 v171, v38, v181
	ds_bpermute_b32 v0, v38, v70
	v_cvt_pk_bf16_f32 v172, v174, v175
	v_pk_mul_f32 v[62:63], v[62:63], v[68:69]
	v_pk_mul_f32 v[174:175], v[24:25], v[176:177]
	ds_bpermute_b32 v1, v38, v71
	v_pk_mul_f32 v[176:177], v[174:175], v[182:183]
	v_cvt_pk_bf16_f32 v2, v62, v63
	v_cvt_pk_bf16_f32 v176, v176, v177
	v_pk_mul_f32 v[62:63], v[24:25], v[64:65]
	ds_write2st64_b32 v39, v172, v176 offset0:141 offset1:150
	v_pk_mul_f32 v[64:65], v[62:63], v[66:67]
	s_waitcnt lgkmcnt(4)
; template <int MODE>
; __device__ void scan_unit(int swave, const Params& p, int j, int b, int h, int dir, char* shm) {
;     ...
;       *(unsigned*)(qin + ti * QS + dp) = pk2(q0 * __expf(cum0), q1 * __expf(cum1));
;       *(unsigned*)(ktil + ti * QS + dp) = pk2(k0 * __expf(-cum0), k1 * __expf(-cum1));
;       koutT[dp * 16 + ti] = f2bf(k0 * __expf(s0 - cum0));
;       koutT[(dp + 1) * 16 + ti] = f2bf(k1 * __expf(s1 - cum1));
;       if (ti == 0) *(float2*)(dec + dp) = make_float2(__expf(s0), __expf(s1));
;       const unsigned v0 = R.v.x, v1 = R.v.y; const int c4 = vg * 4;
;       vT[(c4 + 0) * VS + ti] = (bf16_t)(v0 & 0xffff); vT[(c4 + 1) * VS + ti] = (bf16_t)(v0 >> 16);
;       vT[(c4 + 2) * VS + ti] = (bf16_t)(v1 & 0xffff); vT[(c4 + 3) * VS + ti] = (bf16_t)(v1 >> 16);
;     ...
;   auto compute = [&](const char* buf, bf16_t* obuf) {
;     const bf16_t* qin = (const bf16_t*)buf; const bf16_t* ktil = (const bf16_t*)(buf + OFF_KT); const bf16_t* koutT = (const bf16_t*)(buf + OFF_KO);
;     const bf16_t* vT = (const bf16_t*)(buf + OFF_VT); const float* dec = (const float*)(buf + OFF_DEC);
;     bf16x8 Asc = {0, 0, 0, 0, 0, 0, 0, 0};
;     if (KS == 1 || wk == 0) {
;       f32x4 sc = {0.f, 0.f, 0.f, 0.f};
; #pragma unroll
;       for (int m = 0; m < DK / 32; ++m) {
;         const bf16x8 a = *(const bf16x8*)(ktil + r * QS + m * 32 + q4 * 8);
;         const bf16x8 bb = *(const bf16x8*)(qin + r * QS + m * 32 + q4 * 8);
;         sc = __builtin_amdgcn_mfma_f32_16x16x32_bf16(a, bb, sc, 0, 0, 0);
;       }
;       {
;         const unsigned p01 = pk2(q4 * 4 + 0 > r ? 0.f : sc[0], q4 * 4 + 1 > r ? 0.f : sc[1]);
;         const unsigned p23 = pk2(q4 * 4 + 2 > r ? 0.f : sc[2], q4 * 4 + 3 > r ? 0.f : sc[3]);
;         Asc[0] = (short)(p01 & 0xffff); Asc[1] = (short)(p01 >> 16); Asc[2] = (short)(p23 & 0xffff); Asc[3] = (short)(p23 >> 16);
;       }
;     }
;     bf16x8 Bv[NVT];
; #pragma unroll
;     for (int t = 0; t < NVT; ++t) {
;       const uint2 vv = *(const uint2*)(vT + ((vt0 + t) * 16 + r) * VS + q4 * 4);
;       Bv[t] = (bf16x8){(short)(vv.x & 0xffff), (short)(vv.x >> 16), (short)(vv.y & 0xffff), (short)(vv.y >> 16), 0, 0, 0, 0};
;     }
;     bf16x8 Aq[2];
; #pragma unroll
;     for (int m = 0; m < 2; ++m) {
;       const uint2 lo = *(const uint2*)(qin + r * QS + slab + (2 * m) * 16 + q4 * 4);
	v_sub_f32_e32 v172, v170, v179
	v_cvt_pk_bf16_f32 v57, v64, v65
	v_mul_f32_e32 v172, 0x3fb8aa3b, v172
	ds_write2st64_b32 v39, v2, v57 offset0:94 offset1:103
	v_exp_f32_e32 v172, v172
	s_waitcnt lgkmcnt(3)
	v_sub_f32_e32 v2, v0, v70
	v_sub_f32_e32 v176, v171, v181
	v_mul_f32_e32 v2, 0x3fb8aa3b, v2
	v_mul_f32_e32 v176, 0x3fb8aa3b, v176
	v_exp_f32_e32 v176, v176
	v_exp_f32_e32 v2, v2
	v_mul_f32_e32 v172, v174, v172
	s_waitcnt lgkmcnt(2)
	v_sub_f32_e32 v57, v1, v71
	v_cvt_pk_bf16_f32 v172, v172, s0
	v_mul_f32_e32 v57, 0x3fb8aa3b, v57
	ds_write_b16 v40, v172 offset:40704
	v_exp_f32_e32 v57, v57
	v_mul_f32_e32 v172, v175, v176
	v_mul_f32_e32 v2, v62, v2
	v_cvt_pk_bf16_f32 v172, v172, s0
	v_cvt_pk_bf16_f32 v2, v2, s0
	ds_write_b16 v40, v172 offset:40736
	ds_write_b16 v40, v2 offset:28672
	s_and_saveexec_b64 s[38:39], s[14:15]
	s_cbranch_execz .LBB0_656
	v_mul_f32_e32 v171, 0x3fb8aa3b, v171
	v_mul_f32_e32 v170, 0x3fb8aa3b, v170
	v_exp_f32_e32 v171, v171
	v_exp_f32_e32 v170, v170
	ds_write_b64 v41, v[170:171] offset:47872
.LBB0_656:
	s_or_b64 exec, exec, s[38:39]
	v_mul_f32_e32 v2, v63, v57
	ds_write_b16 v42, v28 offset:42752
	v_cvt_pk_bf16_f32 v2, v2, s0
	ds_write_b16_d16_hi v42, v28 offset:42792
	ds_write_b16 v40, v2 offset:28704
	ds_write_b16 v42, v29 offset:42832
	s_and_saveexec_b64 s[16:17], s[14:15]
	s_cbranch_execz .LBB0_654
	v_mul_f32_e32 v1, 0x3fb8aa3b, v1
	v_mul_f32_e32 v0, 0x3fb8aa3b, v0
	v_exp_f32_e32 v1, v1
	v_exp_f32_e32 v0, v0
	ds_write_b64 v41, v[0:1] offset:35840
.LBB0_654:
	s_or_b64 exec, exec, s[16:17]
	ds_write_b16_d16_hi v42, v29 offset:42872
	ds_read_b128 v[28:31], v46 offset:2304
	ds_read_b128 v[62:65], v46
	ds_read_b128 v[66:69], v46 offset:2368
	ds_read_b128 v[70:73], v46 offset:64
	v_mov_b32_e32 v2, v3
	v_add_u32_e32 v54, 0x2800, v53
	s_waitcnt lgkmcnt(2)
	v_mfma_f32_16x16x32_bf16 v[28:31], v[28:31], v[62:65], 0
	ds_read_b64 v[62:63], v47 offset:6656
	ds_read2_b64 v[74:77], v53 offset1:4
	ds_read2_b64 v[78:81], v53 offset0:8 offset1:12
	v_mov_b32_e32 v64, v3
	v_mov_b32_e32 v65, v3
	s_waitcnt lgkmcnt(3)
	v_mfma_f32_16x16x32_bf16 v[28:31], v[66:69], v[70:73], v[28:31]
	s_waitcnt lgkmcnt(1)
	v_bfi_b32 v76, s30, v76, v76
	s_waitcnt lgkmcnt(0)
	v_bfi_b32 v80, s30, v80, v80
	v_cvt_pk_bf16_f32 v66, v16, v17
	v_cvt_pk_bf16_f32 v67, v18, v19
	v_cvt_pk_bf16_f32 v68, v12, v13
	s_nop 0
	v_cndmask_b32_e64 v0, v28, 0, s[6:7]
	v_cndmask_b32_e64 v1, 0, v29, s[8:9]
	v_cndmask_b32_e64 v28, v30, 0, s[10:11]
	v_cndmask_b32_e64 v29, v31, 0, s[12:13]
	v_cvt_pk_bf16_f32 v0, v0, v1
	v_cvt_pk_bf16_f32 v1, v28, v29
	v_cvt_pk_bf16_f32 v69, v14, v15
	s_nop 0
	v_mfma_f32_16x16x32_bf16 v[28:31], v[0:3], v[62:65], 0
	v_mfma_f32_16x16x32_bf16 v[28:31], v[74:77], v[66:69], v[28:31]
	v_cvt_pk_bf16_f32 v66, v8, v9
	v_cvt_pk_bf16_f32 v67, v10, v11
	v_cvt_pk_bf16_f32 v68, v4, v5
	v_cvt_pk_bf16_f32 v69, v6, v7
	s_nop 1
	v_mfma_f32_16x16x32_bf16 v[28:31], v[78:81], v[66:69], v[28:31]
	s_nop 7
	v_cvt_pk_bf16_f32 v0, v28, s0
	v_cvt_pk_bf16_f32 v1, v29, s0
	ds_write_b16 v48, v0 offset:48128
	ds_write_b16 v48, v1 offset:48392
	v_cvt_pk_bf16_f32 v0, v30, s0
	ds_write_b16 v48, v0 offset:48656
	v_cvt_pk_bf16_f32 v0, v31, s0
	ds_write_b16 v48, v0 offset:48920
	ds_read2st64_b64 v[28:31], v49 offset0:9 offset1:10
	ds_read2st64_b64 v[66:69], v49 offset0:11 offset1:12
	ds_read_b128 v[70:73], v50 offset:11776
	ds_read_b128 v[74:77], v50 offset:11840
	s_waitcnt lgkmcnt(3)
	s_waitcnt lgkmcnt(1)
	v_pk_mul_f32 v[18:19], v[18:19], v[72:73]
	v_pk_mul_f32 v[16:17], v[16:17], v[70:71]
	s_waitcnt lgkmcnt(0)
	v_pk_mul_f32 v[14:15], v[14:15], v[76:77]
	v_pk_mul_f32 v[12:13], v[12:13], v[74:75]
	v_mfma_f32_16x16x16_bf16 v[16:19], v[28:29], v[62:63], v[16:19]
	v_mov_b32_e32 v0, v30
	v_mov_b32_e32 v1, v31
	ds_read_b128 v[28:31], v50 offset:11904
	ds_read_b128 v[70:73], v50 offset:11968
	v_mfma_f32_16x16x16_bf16 v[12:15], v[0:1], v[62:63], v[12:15]
	s_waitcnt lgkmcnt(1)
	v_pk_mul_f32 v[10:11], v[10:11], v[30:31]
	v_pk_mul_f32 v[8:9], v[8:9], v[28:29]
	v_cvt_pk_bf16_f32 v74, v16, v17
	v_cvt_pk_bf16_f32 v75, v18, v19
	v_mfma_f32_16x16x16_bf16 v[28:31], v[66:67], v[62:63], v[8:11]
	s_nop 1
	v_cvt_pk_bf16_f32 v76, v12, v13
	ds_read_b128 v[8:11], v46 offset:14336
	s_waitcnt lgkmcnt(1)
	v_pk_mul_f32 v[6:7], v[6:7], v[72:73]
	v_pk_mul_f32 v[4:5], v[4:5], v[70:71]
	v_cvt_pk_bf16_f32 v77, v14, v15
	s_nop 0
	v_mfma_f32_16x16x16_bf16 v[4:7], v[68:69], v[62:63], v[4:7]
	ds_read_b128 v[62:65], v46 offset:14400
	ds_read_b128 v[66:69], v46 offset:12032
	ds_read_b128 v[70:73], v46 offset:12096
	s_waitcnt lgkmcnt(1)
	v_mfma_f32_16x16x32_bf16 v[8:11], v[8:11], v[66:69], 0
	v_mov_b32_e32 v68, v3
	v_mov_b32_e32 v69, v3
	s_waitcnt lgkmcnt(0)
	v_mfma_f32_16x16x32_bf16 v[8:11], v[62:65], v[70:73], v[8:11]
	s_nop 7
	v_cndmask_b32_e64 v0, v8, 0, s[6:7]
	v_cndmask_b32_e64 v1, 0, v9, s[8:9]
	v_cvt_pk_bf16_f32 v0, v0, v1
	v_cndmask_b32_e64 v1, v10, 0, s[10:11]
	v_cndmask_b32_e64 v2, v11, 0, s[12:13]
	ds_read2_b64 v[8:11], v54 offset0:224 offset1:228
	ds_read2_b64 v[62:65], v54 offset0:232 offset1:236
	v_cvt_pk_bf16_f32 v1, v1, v2
	ds_read_b64 v[66:67], v47 offset:18688
	v_mov_b32_e32 v2, v3
	s_waitcnt lgkmcnt(2)
	v_bfi_b32 v10, s30, v10, v10
	s_waitcnt lgkmcnt(1)
	v_bfi_b32 v64, s30, v64, v64
	s_waitcnt lgkmcnt(0)
	v_mfma_f32_16x16x32_bf16 v[70:73], v[0:3], v[66:69], 0
	v_mfma_f32_16x16x32_bf16 v[8:11], v[8:11], v[74:77], v[70:73]
	s_nop 6
	v_cvt_pk_bf16_f32 v70, v28, v29
	v_cvt_pk_bf16_f32 v71, v30, v31
	v_cvt_pk_bf16_f32 v72, v4, v5
	v_cvt_pk_bf16_f32 v73, v6, v7
	s_nop 1
	v_mfma_f32_16x16x32_bf16 v[8:11], v[62:65], v[70:73], v[8:11]
	v_add_u32_e32 v62, 0x100, v49
	s_nop 6
	v_cvt_pk_bf16_f32 v0, v8, s0
	ds_write_b16 v48, v0 offset:52352
	v_cvt_pk_bf16_f32 v0, v9, s0
	ds_write_b16 v48, v0 offset:52616
	v_cvt_pk_bf16_f32 v0, v10, s0
	ds_write_b16 v48, v0 offset:52880
	v_cvt_pk_bf16_f32 v0, v11, s0
	ds_write_b16 v48, v0 offset:53144
	ds_read2st64_b64 v[70:73], v62 offset0:32 offset1:33
	ds_read2st64_b64 v[74:77], v62 offset0:34 offset1:35
	ds_read_b128 v[8:11], v50 offset:23808
	ds_read_b128 v[78:81], v50 offset:23872
	s_waitcnt lgkmcnt(3)
	s_waitcnt lgkmcnt(1)
	v_pk_mul_f32 v[10:11], v[18:19], v[10:11]
	v_pk_mul_f32 v[8:9], v[16:17], v[8:9]
	s_waitcnt lgkmcnt(0)
	v_pk_mul_f32 v[14:15], v[14:15], v[80:81]
	v_pk_mul_f32 v[12:13], v[12:13], v[78:79]
	v_mfma_f32_16x16x16_bf16 v[8:11], v[70:71], v[66:67], v[8:11]
	v_mov_b32_e32 v0, v72
	v_mov_b32_e32 v1, v73
	ds_read_b128 v[16:19], v50 offset:23936
	ds_read_b128 v[70:73], v50 offset:24000
	v_mfma_f32_16x16x16_bf16 v[12:15], v[0:1], v[66:67], v[12:15]
	s_waitcnt lgkmcnt(1)
	v_pk_mul_f32 v[18:19], v[30:31], v[18:19]
	v_pk_mul_f32 v[16:17], v[28:29], v[16:17]
	s_waitcnt lgkmcnt(0)
	v_pk_mul_f32 v[6:7], v[6:7], v[72:73]
	v_pk_mul_f32 v[4:5], v[4:5], v[70:71]
	v_mfma_f32_16x16x16_bf16 v[16:19], v[74:75], v[66:67], v[16:19]
	s_waitcnt lgkmcnt(0)
	s_barrier
; __device__ __forceinline__ unsigned pk2(float lo, float hi) { f32x2_t v = {lo, hi}; bf16x2_t b = __builtin_convertvector(v, bf16x2_t); return __builtin_bit_cast(unsigned, b); }
; __device__ __forceinline__ float lo_bf(unsigned u) { return __uint_as_float(u << 16); }
; __device__ __forceinline__ float hi_bf(unsigned u) { return __uint_as_float(u & 0xffff0000u); }
; template <int MODE>
; __device__ void scan_unit(int swave, const Params& p, int j, int b, int h, int dir, char* shm) {
;     ...
;   auto ostore = [&](int c, const bf16_t* obuf) {
;     for (int idx = tid; idx < 16 * DV / 4; idx += 512) {
;       const int i = idx / (DV / 4), cc = (idx % (DV / 4)) * 4;
;       uint2 o = *(const uint2*)(obuf + i * OS + cc);
;       if (KS == 2) {
;         const uint2 o2 = *(const uint2*)(obuf + (16 + i) * OS + cc);
;         o.x = pk2(lo_bf(o.x) + lo_bf(o2.x), hi_bf(o.x) + hi_bf(o2.x)); o.y = pk2(lo_bf(o.y) + lo_bf(o2.y), hi_bf(o.y) + hi_bf(o2.y));
;       }
;       *(uint2*)(O + (rowbase + tokof(c, i)) * OLD + cc) = o;
;     }
;     ...
;   auto body = [&](int it, Raw& c0, Raw& c1, Raw& n0, Raw& n1) {
;     touch(c0); touch(c1);
;     __builtin_amdgcn_sched_barrier(0);
;     const int cA = 2 * it + 4 < NCH ? 2 * it + 4 : NCH - 2;
;     load_raw(cA, n0); load_raw(cA + 1, n1);
;     if (it > 0) { ostore(2 * it - 2, obp((it - 1) & 1, 0)); ostore(2 * it - 1, obp((it - 1) & 1, 1)); }
;     stage2(c0, bufp((it + 1) & 1, 0), 0); stage2(c1, bufp((it + 1) & 1, 1), 0);
	v_mfma_f32_16x16x16_bf16 v[4:7], v[76:77], v[66:67], v[4:7]
	s_add_i32 s16, s20, 0x60
	s_and_b64 s[2:3], s[2:3], exec
	s_cselect_b32 s2, s16, 0x7e0
	v_or_b32_e32 v2, s2, v37
	v_sub_u32_e32 v0, 0x7ff, v2
	v_cndmask_b32_e64 v0, v0, v2, s[0:1]
	v_or_b32_e32 v2, 16, v2
	v_ashrrev_i32_e32 v1, 31, v0
	v_sub_u32_e32 v57, 0x7ff, v2
	v_lshl_add_u64 v[0:1], s[46:47], 0, v[0:1]
	v_mov_b64_e32 v[28:29], s[48:49]
	v_cndmask_b32_e64 v64, v57, v2, s[0:1]
	v_mad_u64_u32 v[30:31], s[2:3], v0, s53, v[28:29]
	v_ashrrev_i32_e32 v65, 31, v64
	v_mad_i32_i24 v31, v1, s53, v31
	s_mov_b32 s71, s95
	v_lshl_add_u64 v[64:65], s[46:47], 0, v[64:65]
	v_lshl_add_u64 v[0:1], v[30:31], 0, s[50:51]
	v_lshl_add_u64 v[54:55], v[30:31], 0, s[94:95]
	v_lshl_add_u64 v[30:31], v[30:31], 0, s[70:71]
	v_mad_u64_u32 v[28:29], s[2:3], v64, s53, v[28:29]
	v_lshl_add_u64 v[30:31], v[30:31], 0, v[26:27]
	v_mad_i32_i24 v29, v65, s53, v29
	v_lshl_add_u64 v[54:55], v[54:55], 0, s[50:51]
	v_add_co_u32_e32 v30, vcc, s62, v30
	v_lshl_add_u64 v[66:67], v[28:29], 0, s[94:95]
	v_lshl_add_u64 v[0:1], v[0:1], 0, v[22:23]
	v_lshl_add_u64 v[54:55], v[54:55], 0, v[22:23]
	v_addc_co_u32_e32 v31, vcc, 0, v31, vcc
	v_lshl_add_u64 v[64:65], v[28:29], 0, s[50:51]
	v_lshl_add_u64 v[66:67], v[66:67], 0, s[50:51]
	v_lshl_add_u64 v[64:65], v[64:65], 0, v[22:23]
	v_lshl_add_u64 v[66:67], v[66:67], 0, v[22:23]
	global_load_dword v57, v[0:1], off offset:3136
	global_load_dword v59, v[54:55], off
	s_nop 0
	global_load_dwordx2 v[30:31], v[30:31], off offset:576
	s_nop 0
	global_load_dword v54, v[64:65], off offset:3136
	global_load_dword v55, v[66:67], off
	v_lshl_add_u64 v[0:1], v[28:29], 0, s[70:71]
	v_lshl_add_u64 v[0:1], v[0:1], 0, v[26:27]
	v_add_co_u32_e32 v0, vcc, 0x1000, v0
	s_nop 1
	v_addc_co_u32_e32 v1, vcc, 0, v1, vcc
	global_load_dwordx2 v[28:29], v[0:1], off offset:576
	s_and_saveexec_b64 s[2:3], s[4:5]
	s_cbranch_execz .LBB0_661
	s_sub_i32 vcc_lo, 0x7e0, s20
	s_cmp_lg_u64 s[0:1], 0
	s_cselect_b32 vcc_lo, s20, vcc_lo
	s_add_i32 vcc_lo, vcc_lo, s46
	s_lshl_b32 vcc_lo, vcc_lo, 11
	s_add_u32 s16, s68, vcc_lo
	s_addc_u32 s17, s69, 0
	v_add_u32_e32 v160, v51, v166
	v_add_u32_e32 v161, v52, v166
	ds_read_b64 v[162:163], v160
	ds_read_b64 v[164:165], v161
	s_waitcnt lgkmcnt(1)
	global_store_dwordx2 v167, v[162:163], s[16:17]
	s_waitcnt lgkmcnt(0)
	global_store_dwordx2 v168, v[164:165], s[16:17]
	s_or_b64 exec, exec, s[2:3]
	s_waitcnt vmcnt(8)
	s_branch .Llw_join_647b

; __device__ __forceinline__ unsigned pk2(float lo, float hi) { f32x2_t v = {lo, hi}; bf16x2_t b = __builtin_convertvector(v, bf16x2_t); return __builtin_bit_cast(unsigned, b); }
; __device__ __forceinline__ bf16_t f2bf(float f) { return (bf16_t)(pk2(f, 0.f) & 0xffffu); }
; __device__ __forceinline__ float lo_bf(unsigned u) { return __uint_as_float(u << 16); }
; __device__ __forceinline__ float hi_bf(unsigned u) { return __uint_as_float(u & 0xffff0000u); }
; __device__ __forceinline__ float sigmoidf_(float x) { return __builtin_amdgcn_rcpf(1.f + __expf(-x)); }
; __device__ __forceinline__ float siluf_(float x) { return x * __builtin_amdgcn_rcpf(1.f + __expf(-x)); }
; template <int MODE>
; __device__ void scan_unit(int swave, const Params& p, int j, int b, int h, int dir, char* shm) {
;     ...
;       } else {
;         const float f0 = lbv0 + (1.f - lbv0) * sigmoidf_(lo_bf(R.k)), f1 = lbv1 + (1.f - lbv1) * sigmoidf_(hi_bf(R.k));
;         g0 = __logf(fmaxf(f0, 1e-20f)); g1 = __logf(fmaxf(f1, 1e-20f));
;       }
;       float s0, s1;
;       const float cum0 = row_scan(g0, s0), cum1 = row_scan(g1, s1);
;       float q0, q1, k0, k1;
;       if (MODE == 0) { q0 = lo_bf(R.q); q1 = hi_bf(R.q); k0 = lo_bf(R.k) * 0.125f; k1 = hi_bf(R.k) * 0.125f; }
;       else { q0 = siluf_(lo_bf(R.q)); q1 = siluf_(hi_bf(R.q)); k0 = (1.f - lbv0) * sigmoidf_(-lo_bf(R.k)); k1 = (1.f - lbv1) * sigmoidf_(-hi_bf(R.k)); }
;       *(unsigned*)(qin + ti * QS + dp) = pk2(q0 * __expf(cum0), q1 * __expf(cum1));
;       *(unsigned*)(ktil + ti * QS + dp) = pk2(k0 * __expf(-cum0), k1 * __expf(-cum1));
;       koutT[dp * 16 + ti] = f2bf(k0 * __expf(s0 - cum0));
;       koutT[(dp + 1) * 16 + ti] = f2bf(k1 * __expf(s1 - cum1));
;       if (ti == 0) *(float2*)(dec + dp) = make_float2(__expf(s0), __expf(s1));
;       const unsigned v0 = R.v.x, v1 = R.v.y; const int c4 = vg * 4;
;       vT[(c4 + 0) * VS + ti] = (bf16_t)(v0 & 0xffff); vT[(c4 + 1) * VS + ti] = (bf16_t)(v0 >> 16);
;       vT[(c4 + 2) * VS + ti] = (bf16_t)(v1 & 0xffff); vT[(c4 + 3) * VS + ti] = (bf16_t)(v1 >> 16);
.Llw_join_647b:
	v_lshlrev_b32_e32 v172, 16, v58
	v_lshlrev_b32_e32 v2, 16, v61
	v_mul_f32_e32 v170, 0xbfb8aa3b, v172
	v_mul_f32_e32 v0, 0xbfb8aa3b, v2
	v_exp_f32_e32 v170, v170
	v_exp_f32_e32 v0, v0
	v_and_b32_e32 v178, 0xffff0000, v58
	v_and_b32_e32 v61, 0xffff0000, v61
	v_mul_f32_e32 v171, 0xbfb8aa3b, v178
	v_mul_f32_e32 v1, 0xbfb8aa3b, v61
	v_exp_f32_e32 v171, v171
	v_exp_f32_e32 v1, v1
	v_add_f32_e32 v170, 1.0, v170
	v_add_f32_e32 v0, 1.0, v0
	v_rcp_f32_e32 v170, v170
	v_rcp_f32_e32 v0, v0
	ds_write_b16 v42, v34 offset:6656
	v_mul_f32_e32 v2, 0x3fb8aa3b, v2
	ds_write_b16_d16_hi v42, v34 offset:6696
	v_add_f32_e32 v1, 1.0, v1
	v_add_f32_e32 v171, 1.0, v171
	v_rcp_f32_e32 v1, v1
	v_rcp_f32_e32 v171, v171
	v_fma_f32 v0, v24, v0, v20
	v_fma_f32 v170, v24, v170, v20
	v_max_f32_e32 v0, 0x1e3ce508, v0
	v_max_f32_e32 v170, 0x1e3ce508, v170
	v_cmp_gt_f32_e32 vcc, s26, v0
	v_cmp_gt_f32_e64 s[36:37], s26, v170
	v_fma_f32 v1, v25, v1, v21
	v_fma_f32 v171, v25, v171, v21
	v_max_f32_e32 v1, 0x1e3ce508, v1
	v_max_f32_e32 v171, 0x1e3ce508, v171
	v_cndmask_b32_e64 v63, 0, 32, vcc
	v_cndmask_b32_e64 v174, 0, 32, s[36:37]
	v_ldexp_f32 v0, v0, v63
	v_ldexp_f32 v170, v170, v174
	v_log_f32_e32 v0, v0
	v_log_f32_e32 v170, v170
	v_cmp_gt_f32_e64 s[16:17], s26, v1
	v_cmp_gt_f32_e64 s[38:39], s26, v171
	v_exp_f32_e32 v2, v2
	ds_write_b16 v42, v35 offset:6736
	v_mul_f32_e32 v61, 0x3fb8aa3b, v61
	ds_write_b16_d16_hi v42, v35 offset:6776
	v_cndmask_b32_e64 v63, 0, 32, s[16:17]
	v_cndmask_b32_e64 v175, 0, 32, s[38:39]
	v_mul_f32_e32 v64, 0x3f317217, v0
	v_mul_f32_e32 v174, 0x3f317217, v170
	v_ldexp_f32 v171, v171, v175
	v_ldexp_f32 v1, v1, v63
	v_fma_f32 v174, v170, s31, -v174
	v_fma_f32 v64, v0, s31, -v64
	v_log_f32_e32 v171, v171
	v_log_f32_e32 v1, v1
	v_fmac_f32_e32 v174, 0x3377d1cf, v170
	v_exp_f32_e32 v61, v61
	v_fmac_f32_e32 v174, 0x3f317217, v170
	v_fmac_f32_e32 v64, 0x3377d1cf, v0
	v_cmp_lt_f32_e64 s[40:41], |v170|, s27
	v_fmac_f32_e32 v64, 0x3f317217, v0
	v_mul_f32_e32 v172, 0x3fb8aa3b, v172
	v_cmp_lt_f32_e64 s[18:19], |v0|, s27
	v_exp_f32_e32 v172, v172
	v_cndmask_b32_e32 v63, 0, v157, vcc
	v_cndmask_b32_e64 v170, v170, v174, s[40:41]
	v_add_f32_e32 v2, 1.0, v2
	v_cndmask_b32_e64 v174, 0, v157, s[36:37]
	v_cndmask_b32_e64 v0, v0, v64, s[18:19]
	v_sub_f32_e32 v170, v170, v174
	v_sub_f32_e32 v0, v0, v63
	v_mul_f32_e32 v174, 0x3f317217, v171
	v_mul_f32_e32 v63, 0x3f317217, v1
	v_mul_f32_e32 v175, 0x3fb8aa3b, v178
	v_lshlrev_b32_e32 v64, 16, v60
	v_fma_f32 v174, v171, s31, -v174
	v_and_b32_e32 v65, 0xffff0000, v60
	v_exp_f32_e32 v178, v175
	v_rcp_f32_e32 v60, v2
	v_fmac_f32_e32 v174, 0x3377d1cf, v171
	v_add_f32_e32 v2, 1.0, v61
	v_fmac_f32_e32 v174, 0x3f317217, v171
	v_fma_f32 v63, v1, s31, -v63
	v_cmp_lt_f32_e64 s[36:37], |v171|, s27
	v_rcp_f32_e32 v61, v2
	v_add_f32_e32 v172, 1.0, v172
	v_mul_f32_e32 v2, 0xbfb8aa3b, v64
	v_rcp_f32_e32 v180, v172
	v_fmac_f32_e32 v63, 0x3377d1cf, v1
	v_cndmask_b32_e64 v171, v171, v174, s[36:37]
	v_exp_f32_e32 v2, v2
	v_cndmask_b32_e64 v174, 0, v157, s[38:39]
	v_mul_f32_e32 v66, 0xbfb8aa3b, v65
	v_sub_f32_e32 v171, v171, v174
	v_fmac_f32_e32 v63, 0x3f317217, v1
	v_lshlrev_b32_e32 v174, 16, v56
	v_add_f32_e32 v172, 1.0, v178
	v_cmp_lt_f32_e64 vcc, |v1|, s27
	v_and_b32_e32 v175, 0xffff0000, v56
	v_exp_f32_e32 v67, v66
	v_rcp_f32_e32 v181, v172
	v_add_f32_e32 v2, 1.0, v2
	v_mul_f32_e32 v172, 0xbfb8aa3b, v174
	v_cndmask_b32_e32 v1, v1, v63, vcc
	v_exp_f32_e32 v172, v172
	v_cndmask_b32_e64 v63, 0, v157, s[16:17]
	v_mul_f32_e32 v176, 0xbfb8aa3b, v175
	v_sub_f32_e32 v1, v1, v63
	v_exp_f32_e32 v176, v176
	v_add_f32_dpp v0, v0, v0 row_shr:1 row_mask:0xf bank_mask:0xf bound_ctrl:1
	v_add_f32_dpp v170, v170, v170 row_shr:1 row_mask:0xf bank_mask:0xf bound_ctrl:1
	v_rcp_f32_e32 v66, v2
	v_add_f32_dpp v171, v171, v171 row_shr:1 row_mask:0xf bank_mask:0xf bound_ctrl:1
	v_add_f32_dpp v1, v1, v1 row_shr:1 row_mask:0xf bank_mask:0xf bound_ctrl:1
	v_add_f32_e32 v172, 1.0, v172
	v_add_f32_e32 v2, 1.0, v67
	v_add_f32_dpp v170, v170, v170 row_shr:2 row_mask:0xf bank_mask:0xf bound_ctrl:1
	v_add_f32_dpp v0, v0, v0 row_shr:2 row_mask:0xf bank_mask:0xf bound_ctrl:1
	v_add_f32_dpp v171, v171, v171 row_shr:2 row_mask:0xf bank_mask:0xf bound_ctrl:1
	v_add_f32_dpp v1, v1, v1 row_shr:2 row_mask:0xf bank_mask:0xf bound_ctrl:1
	v_rcp_f32_e32 v184, v172
	v_rcp_f32_e32 v67, v2
	v_add_f32_e32 v172, 1.0, v176
	v_add_f32_dpp v0, v0, v0 row_shr:4 row_mask:0xf bank_mask:0xf bound_ctrl:1
	v_add_f32_dpp v170, v170, v170 row_shr:4 row_mask:0xf bank_mask:0xf bound_ctrl:1
	v_add_f32_dpp v1, v1, v1 row_shr:4 row_mask:0xf bank_mask:0xf bound_ctrl:1
	v_add_f32_dpp v171, v171, v171 row_shr:4 row_mask:0xf bank_mask:0xf bound_ctrl:1
	v_pk_mul_f32 v[60:61], v[24:25], v[60:61]
	v_rcp_f32_e32 v185, v172
	v_add_f32_dpp v63, v0, v0 row_shr:8 row_mask:0xf bank_mask:0xf bound_ctrl:1
	v_add_f32_dpp v183, v170, v170 row_shr:8 row_mask:0xf bank_mask:0xf bound_ctrl:1
	v_add_f32_dpp v70, v1, v1 row_shr:8 row_mask:0xf bank_mask:0xf bound_ctrl:1
	v_add_f32_dpp v188, v171, v171 row_shr:8 row_mask:0xf bank_mask:0xf bound_ctrl:1
	v_mul_f32_e32 v2, 0x3fb8aa3b, v70
	v_mul_f32_e32 v178, 0x3fb8aa3b, v183
	v_mul_f32_e32 v68, 0x3fb8aa3b, v63
	v_mul_f32_e32 v172, 0x3fb8aa3b, v188
	v_exp_f32_e32 v69, v2
	v_exp_f32_e32 v186, v178
	v_mul_f32_e32 v2, 0xbfb8aa3b, v63
	v_exp_f32_e32 v187, v172
	v_exp_f32_e32 v68, v68
	v_mul_f32_e32 v172, 0xbfb8aa3b, v183
	v_pk_mul_f32 v[64:65], v[66:67], v[64:65]
	v_pk_mul_f32 v[174:175], v[184:185], v[174:175]
	v_exp_f32_e32 v184, v172
	v_exp_f32_e32 v66, v2
	v_mul_f32_e32 v172, 0xbfb8aa3b, v188
	v_mul_f32_e32 v2, 0xbfb8aa3b, v70
	v_exp_f32_e32 v185, v172
	v_exp_f32_e32 v67, v2
	ds_bpermute_b32 v170, v38, v183
	ds_bpermute_b32 v0, v38, v63
	v_pk_mul_f32 v[174:175], v[174:175], v[186:187]
	ds_bpermute_b32 v1, v38, v70
	ds_bpermute_b32 v171, v38, v188
	v_pk_mul_f32 v[64:65], v[64:65], v[68:69]
	v_cvt_pk_bf16_f32 v172, v174, v175
	v_cvt_pk_bf16_f32 v2, v64, v65
	v_pk_mul_f32 v[174:175], v[24:25], v[180:181]
	v_pk_mul_f32 v[64:65], v[60:61], v[66:67]
	v_pk_mul_f32 v[180:181], v[174:175], v[184:185]
	v_cvt_pk_bf16_f32 v64, v64, v65
	v_cvt_pk_bf16_f32 v176, v180, v181
	ds_write2st64_b32 v39, v2, v64 offset1:9
	ds_write2st64_b32 v39, v172, v176 offset0:47 offset1:56
	s_waitcnt lgkmcnt(4)
; __device__ __forceinline__ unsigned pk2(float lo, float hi) { f32x2_t v = {lo, hi}; bf16x2_t b = __builtin_convertvector(v, bf16x2_t); return __builtin_bit_cast(unsigned, b); }
; __device__ __forceinline__ bf16_t f2bf(float f) { return (bf16_t)(pk2(f, 0.f) & 0xffffu); }
; __device__ __forceinline__ float lo_bf(unsigned u) { return __uint_as_float(u << 16); }
; __device__ __forceinline__ float hi_bf(unsigned u) { return __uint_as_float(u & 0xffff0000u); }
; __device__ __forceinline__ float sigmoidf_(float x) { return __builtin_amdgcn_rcpf(1.f + __expf(-x)); }
; __device__ __forceinline__ float siluf_(float x) { return x * __builtin_amdgcn_rcpf(1.f + __expf(-x)); }
; template <int MODE>
; __device__ void scan_unit(int swave, const Params& p, int j, int b, int h, int dir, char* shm) {
;     ...
;       float s0, s1;
;       const float cum0 = row_scan(g0, s0), cum1 = row_scan(g1, s1);
;       float q0, q1, k0, k1;
;       if (MODE == 0) { q0 = lo_bf(R.q); q1 = hi_bf(R.q); k0 = lo_bf(R.k) * 0.125f; k1 = hi_bf(R.k) * 0.125f; }
;       else { q0 = siluf_(lo_bf(R.q)); q1 = siluf_(hi_bf(R.q)); k0 = (1.f - lbv0) * sigmoidf_(-lo_bf(R.k)); k1 = (1.f - lbv1) * sigmoidf_(-hi_bf(R.k)); }
;       *(unsigned*)(qin + ti * QS + dp) = pk2(q0 * __expf(cum0), q1 * __expf(cum1));
;       *(unsigned*)(ktil + ti * QS + dp) = pk2(k0 * __expf(-cum0), k1 * __expf(-cum1));
;       koutT[dp * 16 + ti] = f2bf(k0 * __expf(s0 - cum0));
;       koutT[(dp + 1) * 16 + ti] = f2bf(k1 * __expf(s1 - cum1));
;       if (ti == 0) *(float2*)(dec + dp) = make_float2(__expf(s0), __expf(s1));
;       const unsigned v0 = R.v.x, v1 = R.v.y; const int c4 = vg * 4;
;       vT[(c4 + 0) * VS + ti] = (bf16_t)(v0 & 0xffff); vT[(c4 + 1) * VS + ti] = (bf16_t)(v0 >> 16);
;       vT[(c4 + 2) * VS + ti] = (bf16_t)(v1 & 0xffff); vT[(c4 + 3) * VS + ti] = (bf16_t)(v1 >> 16);
	v_sub_f32_e32 v2, v0, v63
	v_sub_f32_e32 v172, v170, v183
	v_mul_f32_e32 v2, 0x3fb8aa3b, v2
	v_mul_f32_e32 v172, 0x3fb8aa3b, v172
	v_exp_f32_e32 v2, v2
	v_exp_f32_e32 v172, v172
	s_waitcnt lgkmcnt(3)
	v_sub_f32_e32 v63, v1, v70
	s_waitcnt lgkmcnt(2)
	v_sub_f32_e32 v176, v171, v188
	v_mul_f32_e32 v63, 0x3fb8aa3b, v63
	v_mul_f32_e32 v176, 0x3fb8aa3b, v176
	v_exp_f32_e32 v63, v63
	v_exp_f32_e32 v176, v176
	v_mul_f32_e32 v2, v60, v2
	v_mul_f32_e32 v172, v174, v172
	v_cvt_pk_bf16_f32 v2, v2, s0
	v_cvt_pk_bf16_f32 v172, v172, s0
	ds_write_b16 v40, v2 offset:4608
	ds_write_b16 v40, v172 offset:16640
	v_mul_f32_e32 v2, v61, v63
	v_mul_f32_e32 v172, v175, v176
	v_cvt_pk_bf16_f32 v2, v2, s0
	v_cvt_pk_bf16_f32 v172, v172, s0
	ds_write_b16 v40, v2 offset:4640
	ds_write_b16 v40, v172 offset:16672
	s_and_saveexec_b64 s[2:3], s[14:15]
	s_cbranch_execz .LBB0_663
	v_mul_f32_e32 v1, 0x3fb8aa3b, v1
	v_mul_f32_e32 v0, 0x3fb8aa3b, v0
	v_exp_f32_e32 v1, v1
	v_exp_f32_e32 v0, v0
	ds_write_b64 v41, v[0:1] offset:11776
.LBB0_663:
	s_or_b64 exec, exec, s[2:3]
	s_and_saveexec_b64 s[2:3], s[14:15]
	s_cbranch_execz .Lil_t_646
	v_mul_f32_e32 v171, 0x3fb8aa3b, v171
	v_mul_f32_e32 v170, 0x3fb8aa3b, v170
	v_exp_f32_e32 v171, v171
	v_exp_f32_e32 v170, v170
	ds_write_b64 v41, v[170:171] offset:23808
.Lil_t_646:
	s_or_b64 exec, exec, s[2:3]
	s_branch .LBB0_646

; template <int MODE>
; __device__ void scan_unit(int swave, const Params& p, int j, int b, int h, int dir, char* shm) {
;     ...
;   auto compute = [&](const char* buf, bf16_t* obuf) {
;     const bf16_t* qin = (const bf16_t*)buf; const bf16_t* ktil = (const bf16_t*)(buf + OFF_KT); const bf16_t* koutT = (const bf16_t*)(buf + OFF_KO);
;     const bf16_t* vT = (const bf16_t*)(buf + OFF_VT); const float* dec = (const float*)(buf + OFF_DEC);
;     bf16x8 Asc = {0, 0, 0, 0, 0, 0, 0, 0};
;     if (KS == 1 || wk == 0) {
;       f32x4 sc = {0.f, 0.f, 0.f, 0.f};
; #pragma unroll
;       for (int m = 0; m < DK / 32; ++m) {
;         const bf16x8 a = *(const bf16x8*)(ktil + r * QS + m * 32 + q4 * 8);
;         const bf16x8 bb = *(const bf16x8*)(qin + r * QS + m * 32 + q4 * 8);
;         sc = __builtin_amdgcn_mfma_f32_16x16x32_bf16(a, bb, sc, 0, 0, 0);
;       }
;       {
;         const unsigned p01 = pk2(q4 * 4 + 0 > r ? 0.f : sc[0], q4 * 4 + 1 > r ? 0.f : sc[1]);
;         const unsigned p23 = pk2(q4 * 4 + 2 > r ? 0.f : sc[2], q4 * 4 + 3 > r ? 0.f : sc[3]);
;         Asc[0] = (short)(p01 & 0xffff); Asc[1] = (short)(p01 >> 16); Asc[2] = (short)(p23 & 0xffff); Asc[3] = (short)(p23 >> 16);
;       }
;     }
;     bf16x8 Bv[NVT];
; #pragma unroll
;     for (int t = 0; t < NVT; ++t) {
;       const uint2 vv = *(const uint2*)(vT + ((vt0 + t) * 16 + r) * VS + q4 * 4);
;       Bv[t] = (bf16x8){(short)(vv.x & 0xffff), (short)(vv.x >> 16), (short)(vv.y & 0xffff), (short)(vv.y >> 16), 0, 0, 0, 0};
;     }
;     bf16x8 Aq[2];
; #pragma unroll
;     for (int m = 0; m < 2; ++m) {
;       const uint2 lo = *(const uint2*)(qin + r * QS + slab + (2 * m) * 16 + q4 * 4);
;       const uint2 hi = *(const uint2*)(qin + r * QS + slab + (2 * m + 1) * 16 + q4 * 4);
;       Aq[m] = (bf16x8){(short)(lo.x & 0xffff), (short)(lo.x >> 16), (short)(lo.y & 0xffff), (short)(lo.y >> 16),
;                        (short)(hi.x & 0xffff), (short)(hi.x >> 16), (short)(hi.y & 0xffff), (short)(hi.y >> 16)};
;     }
;     f32x4 o[NVT];
; #pragma unroll
;     for (int t = 0; t < NVT; ++t) {
;       o[t] = (f32x4){0.f, 0.f, 0.f, 0.f};
;       if (KS == 1 || wk == 0) o[t] = __builtin_amdgcn_mfma_f32_16x16x32_bf16(Asc, Bv[t], o[t], 0, 0, 0);
;     }
; #pragma unroll
;     for (int m = 0; m < 2; ++m)
; #pragma unroll
;       for (int t = 0; t < NVT; ++t) {
;         const f32x4 s0 = S[2 * m][t], s1 = S[2 * m + 1][t];
.LBB0_676:
	ds_write_b16 v104, v92 offset:18688
	ds_write_b16_d16_hi v104, v92 offset:18728
	ds_write_b16 v104, v93 offset:18768
	ds_write_b16_d16_hi v104, v93 offset:18808
	ds_read_b128 v[20:23], v108 offset:26368
	ds_read_b128 v[24:27], v108 offset:24064
	ds_read_b128 v[28:31], v108 offset:26432
	ds_read_b128 v[32:35], v108 offset:24128
	v_add_u32_e32 v0, 0x5800, v115
	s_add_i32 s35, s35, 2
	s_waitcnt lgkmcnt(2)
	v_mfma_f32_16x16x32_bf16 v[20:23], v[20:23], v[24:27], 0
	ds_read_b64 v[24:25], v109 offset:30720
	ds_read2_b64 v[120:123], v0 offset0:192 offset1:196
	ds_read2_b64 v[126:129], v0 offset0:200 offset1:204
	v_mov_b32_e32 v26, v3
	v_mov_b32_e32 v27, v3
	s_waitcnt lgkmcnt(3)
	v_mfma_f32_16x16x32_bf16 v[20:23], v[28:31], v[32:35], v[20:23]
	s_waitcnt lgkmcnt(1)
	v_bfi_b32 v122, s30, v122, v122
	s_waitcnt lgkmcnt(0)
	v_bfi_b32 v128, s30, v128, v128
	v_cvt_pk_bf16_f32 v28, v40, v41
	v_cvt_pk_bf16_f32 v29, v42, v43
	v_cvt_pk_bf16_f32 v30, v44, v45
	s_nop 0
	v_cndmask_b32_e64 v0, v20, 0, s[6:7]
	v_cndmask_b32_e64 v1, 0, v21, s[8:9]
	v_cndmask_b32_e64 v2, v22, 0, s[10:11]
	v_cndmask_b32_e64 v20, v23, 0, s[12:13]
	v_cvt_pk_bf16_f32 v0, v0, v1
	v_cvt_pk_bf16_f32 v1, v2, v20
	v_mov_b32_e32 v2, v3
	v_cvt_pk_bf16_f32 v31, v46, v47
	s_and_b64 vcc, exec, s[72:73]
	v_mfma_f32_16x16x32_bf16 v[20:23], v[0:3], v[24:27], 0
	v_mfma_f32_16x16x32_bf16 v[20:23], v[120:123], v[28:31], v[20:23]
	v_cvt_pk_bf16_f32 v28, v48, v49
	v_cvt_pk_bf16_f32 v29, v50, v51
	v_cvt_pk_bf16_f32 v30, v36, v37
	v_cvt_pk_bf16_f32 v31, v38, v39
	s_nop 1
	v_mfma_f32_16x16x32_bf16 v[20:23], v[126:129], v[28:31], v[20:23]
	s_nop 7
	v_cvt_pk_bf16_f32 v0, v20, s0
	ds_write_b16 v110, v0 offset:56576
	v_cvt_pk_bf16_f32 v0, v21, s0
	ds_write_b16 v110, v0 offset:56840
	v_cvt_pk_bf16_f32 v0, v22, s0
	ds_write_b16 v110, v0 offset:57104
	v_cvt_pk_bf16_f32 v0, v23, s0
	ds_write_b16 v110, v0 offset:57368
	ds_read2st64_b64 v[20:23], v111 offset0:56 offset1:57
	ds_read2st64_b64 v[28:31], v111 offset0:58 offset1:59
	ds_read_b128 v[32:35], v112 offset:35840
	ds_read_b128 v[120:123], v112 offset:35904
	s_waitcnt lgkmcnt(3)
	v_mov_b32_e32 v0, v20
	v_mov_b32_e32 v1, v21
	s_waitcnt lgkmcnt(1)
	v_pk_mul_f32 v[34:35], v[42:43], v[34:35]
	v_pk_mul_f32 v[32:33], v[40:41], v[32:33]
	s_waitcnt lgkmcnt(0)
	v_pk_mul_f32 v[20:21], v[44:45], v[120:121]
	ds_read_b128 v[40:43], v112 offset:35968
	v_mfma_f32_16x16x16_bf16 v[32:35], v[0:1], v[24:25], v[32:35]
	v_mov_b32_e32 v0, v22
	v_mov_b32_e32 v1, v23
	v_pk_mul_f32 v[22:23], v[46:47], v[122:123]
	ds_read_b128 v[44:47], v112 offset:36032
	s_waitcnt lgkmcnt(1)
	v_pk_mul_f32 v[42:43], v[50:51], v[42:43]
	v_mfma_f32_16x16x16_bf16 v[20:23], v[0:1], v[24:25], v[20:23]
	v_pk_mul_f32 v[40:41], v[48:49], v[40:41]
	v_mov_b32_e32 v122, v3
	v_mov_b32_e32 v123, v3
	v_mfma_f32_16x16x16_bf16 v[40:43], v[28:29], v[24:25], v[40:43]
	v_mov_b32_e32 v0, v30
	v_mov_b32_e32 v1, v31
	ds_read_b128 v[28:31], v108 offset:38400
	s_waitcnt lgkmcnt(1)
	v_pk_mul_f32 v[38:39], v[38:39], v[46:47]
	v_pk_mul_f32 v[36:37], v[36:37], v[44:45]
	s_nop 1
	v_mfma_f32_16x16x16_bf16 v[24:27], v[0:1], v[24:25], v[36:39]
	s_nop 2
	ds_read_b128 v[36:39], v108 offset:38464
	ds_read_b128 v[44:47], v108 offset:36096
	ds_read_b128 v[48:51], v108 offset:36160
	s_waitcnt lgkmcnt(1)
	v_mfma_f32_16x16x32_bf16 v[28:31], v[28:31], v[44:47], 0
	s_waitcnt lgkmcnt(0)
	v_mfma_f32_16x16x32_bf16 v[28:31], v[36:39], v[48:51], v[28:31]
	v_add_u32_e32 v36, 0x8800, v115
	v_cvt_pk_bf16_f32 v48, v32, v33
	v_cvt_pk_bf16_f32 v49, v34, v35
	v_cvt_pk_bf16_f32 v50, v20, v21
	v_cvt_pk_bf16_f32 v51, v22, v23
	s_nop 2
	v_cndmask_b32_e64 v0, v28, 0, s[6:7]
	v_cndmask_b32_e64 v1, 0, v29, s[8:9]
	v_cvt_pk_bf16_f32 v0, v0, v1
	v_cndmask_b32_e64 v1, v30, 0, s[10:11]
	v_cndmask_b32_e64 v2, v31, 0, s[12:13]
	ds_read2_b64 v[28:31], v36 offset0:160 offset1:164
	ds_read2_b64 v[36:39], v36 offset0:168 offset1:172
	v_cvt_pk_bf16_f32 v1, v1, v2
	ds_read_b64 v[120:121], v109 offset:42752
	v_mov_b32_e32 v2, v3
	s_waitcnt lgkmcnt(2)
	v_bfi_b32 v30, s30, v30, v30
	s_waitcnt lgkmcnt(1)
	v_bfi_b32 v38, s30, v38, v38
	s_waitcnt lgkmcnt(0)
	v_mfma_f32_16x16x32_bf16 v[44:47], v[0:3], v[120:123], 0
	v_mfma_f32_16x16x32_bf16 v[28:31], v[28:31], v[48:51], v[44:47]
	s_nop 6
	v_cvt_pk_bf16_f32 v44, v40, v41
	v_cvt_pk_bf16_f32 v45, v42, v43
	v_cvt_pk_bf16_f32 v46, v24, v25
	v_cvt_pk_bf16_f32 v47, v26, v27
	s_nop 1
	v_mfma_f32_16x16x32_bf16 v[28:31], v[36:39], v[44:47], v[28:31]
	s_nop 7
	v_cvt_pk_bf16_f32 v0, v28, s0
	ds_write_b16 v110, v0 offset:60800
	v_cvt_pk_bf16_f32 v0, v29, s0
	ds_write_b16 v110, v0 offset:61064
	v_cvt_pk_bf16_f32 v0, v30, s0
	ds_write_b16 v110, v0 offset:61328
	v_cvt_pk_bf16_f32 v0, v31, s0
	ds_write_b16 v110, v0 offset:61592
	ds_read2st64_b64 v[28:31], v124 offset0:79 offset1:80
	ds_read2st64_b64 v[36:39], v124 offset0:81 offset1:82
	ds_read_b128 v[44:47], v112 offset:47872
	ds_read_b128 v[124:127], v112 offset:47936
	s_waitcnt lgkmcnt(3)
	s_waitcnt lgkmcnt(1)
	v_pk_mul_f32 v[34:35], v[34:35], v[46:47]
	v_pk_mul_f32 v[32:33], v[32:33], v[44:45]
	s_waitcnt lgkmcnt(0)
	v_pk_mul_f32 v[22:23], v[22:23], v[126:127]
	v_pk_mul_f32 v[20:21], v[20:21], v[124:125]
	v_mfma_f32_16x16x16_bf16 v[48:51], v[28:29], v[120:121], v[32:35]
	v_mov_b32_e32 v0, v30
	v_mov_b32_e32 v1, v31
	ds_read_b128 v[28:31], v112 offset:48064
	s_nop 0
	v_mfma_f32_16x16x16_bf16 v[44:47], v[0:1], v[120:121], v[20:23]
	s_nop 1
	ds_read_b128 v[20:23], v112 offset:48000
	s_waitcnt lgkmcnt(0)
	s_barrier
	s_waitcnt lgkmcnt(0)
	v_pk_mul_f32 v[22:23], v[42:43], v[22:23]
	v_pk_mul_f32 v[20:21], v[40:41], v[20:21]
	s_nop 1
	v_mfma_f32_16x16x16_bf16 v[40:43], v[36:37], v[120:121], v[20:23]
	v_mov_b32_e32 v0, v38
	v_mov_b32_e32 v1, v39
	s_nop 0
	v_pk_mul_f32 v[22:23], v[26:27], v[30:31]
	v_pk_mul_f32 v[20:21], v[24:25], v[28:29]
	s_nop 1
	v_mfma_f32_16x16x16_bf16 v[36:39], v[0:1], v[120:121], v[20:23]
	s_cbranch_vccnz .LBB0_695

; __device__ __forceinline__ float lo_bf(unsigned u) { return __uint_as_float(u << 16); }
; __device__ __forceinline__ float hi_bf(unsigned u) { return __uint_as_float(u & 0xffff0000u); }
; template <int MODE>
; __device__ void scan_unit(int swave, const Params& p, int j, int b, int h, int dir, char* shm) {
;     ...
;       if (MODE == 0) {
;         float z0 = bav0, z1 = bav1;
;         const unsigned lw[8] = {R.lr0.x, R.lr0.y, R.lr0.z, R.lr0.w, R.lr1.x, R.lr1.y, R.lr1.z, R.lr1.w};
; #pragma unroll
;         for (int e = 0; e < 8; ++e) {
;           const float a0 = lo_bf(lw[e]), a1 = hi_bf(lw[e]);
;           z0 += a0 * wa2r[4 * e] + a1 * wa2r[4 * e + 2];
;           z1 += a0 * wa2r[4 * e + 1] + a1 * wa2r[4 * e + 3];
;         }
;         g0 = (fminf(z0, 0.f) - __logf(1.f + __expf(-fabsf(z0)))) * (1.f / 16.f);
;         g1 = (fminf(z1, 0.f) - __logf(1.f + __expf(-fabsf(z1)))) * (1.f / 16.f);
.Llw_join_677a:
	v_and_b32_e32 v171, 0xffff0000, v8
	v_and_b32_e32 v1, 0xffff0000, v16
	v_lshlrev_b32_e32 v170, 16, v8
	v_lshlrev_b32_e32 v0, 16, v16
	v_mul_f32_e32 v172, v54, v171
	v_mul_f32_e32 v2, v54, v1
	v_mul_f32_e32 v171, v55, v171
	v_mul_f32_e32 v1, v55, v1
	v_fmac_f32_e32 v171, v53, v170
	v_fmac_f32_e32 v1, v53, v0
	v_and_b32_e32 v178, 0xffff0000, v9
	v_and_b32_e32 v16, 0xffff0000, v17
	v_fmac_f32_e32 v172, v52, v170
	v_fmac_f32_e32 v2, v52, v0
	v_add_f32_e32 v170, v81, v171
	v_add_f32_e32 v0, v81, v1
	v_lshlrev_b32_e32 v171, 16, v9
	v_lshlrev_b32_e32 v1, 16, v17
	v_mul_f32_e32 v179, v58, v178
	v_mul_f32_e32 v17, v58, v16
	v_mul_f32_e32 v178, v59, v178
	v_mul_f32_e32 v16, v59, v16
	v_fmac_f32_e32 v178, v57, v171
	v_fmac_f32_e32 v16, v57, v1
	v_add_f32_e32 v172, v80, v172
	v_add_f32_e32 v2, v80, v2
	v_fmac_f32_e32 v179, v56, v171
	v_fmac_f32_e32 v17, v56, v1
	v_add_f32_e32 v170, v178, v170
	v_add_f32_e32 v0, v16, v0
	v_and_b32_e32 v178, 0xffff0000, v10
	v_and_b32_e32 v16, 0xffff0000, v18
	v_add_f32_e32 v172, v179, v172
	v_add_f32_e32 v2, v17, v2
	v_lshlrev_b32_e32 v171, 16, v10
	v_lshlrev_b32_e32 v1, 16, v18
	v_mul_f32_e32 v179, v68, v178
	v_mul_f32_e32 v178, v69, v178
	v_mul_f32_e32 v17, v68, v16
	v_fmac_f32_e32 v178, v77, v171
	v_mul_f32_e32 v16, v69, v16
	v_fmac_f32_e32 v179, v76, v171
	v_fmac_f32_e32 v16, v77, v1
	v_add_f32_e32 v170, v178, v170
	v_fmac_f32_e32 v17, v76, v1
	v_and_b32_e32 v178, 0xffff0000, v11
	v_add_f32_e32 v0, v16, v0
	v_add_f32_e32 v172, v179, v172
	v_and_b32_e32 v16, 0xffff0000, v19
	v_lshlrev_b32_e32 v171, 16, v11
	v_add_f32_e32 v2, v17, v2
	v_mul_f32_e32 v179, v72, v178
	v_lshlrev_b32_e32 v1, 16, v19
	v_mul_f32_e32 v178, v73, v178
	v_mul_f32_e32 v17, v72, v16
	v_fmac_f32_e32 v179, v70, v171
	v_mul_f32_e32 v16, v73, v16
	v_fmac_f32_e32 v178, v71, v171
	v_fmac_f32_e32 v17, v70, v1
	v_lshlrev_b32_e32 v171, 16, v4
	v_fmac_f32_e32 v16, v71, v1
	v_and_b32_e32 v174, 0xffff0000, v4
	v_lshlrev_b32_e32 v1, 16, v12
	v_add_f32_e32 v170, v178, v170
	v_and_b32_e32 v12, 0xffff0000, v12
	v_mul_f32_e32 v178, v62, v174
	v_add_f32_e32 v0, v16, v0
	v_mul_f32_e32 v174, v63, v174
	v_mul_f32_e32 v16, v62, v12
	v_add_f32_e32 v172, v179, v172
	v_mul_f32_e32 v12, v63, v12
	v_fmac_f32_e32 v178, v60, v171
	v_fmac_f32_e32 v174, v61, v171
	v_add_f32_e32 v2, v17, v2
	v_and_b32_e32 v171, 0xffff0000, v5
	v_fmac_f32_e32 v16, v60, v1
	v_add_f32_e32 v172, v178, v172
	v_fmac_f32_e32 v12, v61, v1
	v_add_f32_e32 v178, v174, v170
	v_and_b32_e32 v1, 0xffff0000, v13
	v_lshlrev_b32_e32 v170, 16, v5
	v_add_f32_e32 v2, v16, v2
	v_mul_f32_e32 v174, v66, v171
	v_add_f32_e32 v16, v12, v0
	v_fmac_f32_e32 v174, v64, v170
	v_lshlrev_b32_e32 v0, 16, v13
	v_add_f32_e32 v172, v174, v172
	v_mul_f32_e32 v12, v66, v1
	v_mul_f32_e32 v179, v67, v171
	v_fmac_f32_e32 v12, v64, v0
	v_and_b32_e32 v175, 0xffff0000, v7
	v_add_f32_e32 v2, v12, v2
	v_and_b32_e32 v174, 0xffff0000, v6
	v_mul_f32_e32 v17, v67, v1
	v_fmac_f32_e32 v179, v65, v170
	v_and_b32_e32 v13, 0xffff0000, v15
	v_lshlrev_b32_e32 v171, 16, v7
	v_and_b32_e32 v12, 0xffff0000, v14
	v_lshlrev_b32_e32 v170, 16, v6
	v_fmac_f32_e32 v17, v65, v0
	v_pk_mul_f32 v[176:177], v[78:79], v[174:175]
	v_lshlrev_b32_e32 v1, 16, v15
	v_pk_mul_f32 v[174:175], v[88:89], v[174:175]
	v_lshlrev_b32_e32 v0, 16, v14
	v_pk_fma_f32 v[176:177], v[74:75], v[170:171], v[176:177]
	v_pk_mul_f32 v[14:15], v[78:79], v[12:13]
	v_pk_fma_f32 v[170:171], v[86:87], v[170:171], v[174:175]
	v_pk_mul_f32 v[12:13], v[88:89], v[12:13]
	v_add_f32_e32 v172, v176, v172
	v_add_f32_e32 v172, v177, v172
	v_pk_fma_f32 v[14:15], v[74:75], v[0:1], v[14:15]
	v_mul_f32_e64 v176, |v172|, s56
	v_pk_fma_f32 v[0:1], v[86:87], v[0:1], v[12:13]
	v_exp_f32_e32 v176, v176
	v_add_f32_e32 v2, v14, v2
	v_add_f32_e32 v177, v179, v178
	v_add_f32_e32 v2, v15, v2
	v_add_f32_e32 v170, v170, v177
	v_mul_f32_e64 v14, |v2|, s56
	v_add_f32_e32 v170, v171, v170
	v_exp_f32_e32 v14, v14
	v_add_f32_e32 v174, 1.0, v176
	v_add_f32_e32 v15, v17, v16
	v_cmp_gt_f32_e64 s[36:37], s26, v174
	v_add_f32_e32 v0, v0, v15
	v_min_f32_e32 v171, 0, v172
	v_add_f32_e32 v0, v1, v0
	v_lshlrev_b32_e32 v176, 16, v116
	v_add_f32_e32 v12, 1.0, v14
	v_cndmask_b32_e64 v175, 0, 32, s[36:37]
	v_cmp_gt_f32_e32 vcc, s26, v12
	v_ldexp_f32 v174, v174, v175
	v_min_f32_e32 v1, 0, v2
	v_log_f32_e32 v174, v174
	v_lshlrev_b32_e32 v14, 16, v118
	v_mul_f32_e64 v175, |v170|, s56
	v_cndmask_b32_e64 v13, 0, 32, vcc
	v_exp_f32_e32 v175, v175
	v_ldexp_f32 v12, v12, v13
	v_min_f32_e32 v170, 0, v170
	v_log_f32_e32 v12, v12
	v_mul_f32_e32 v172, 0x3f317217, v174
	v_mul_f32_e64 v13, |v0|, s56
	v_fma_f32 v172, v174, s31, -v172
	v_fmac_f32_e32 v172, 0x3377d1cf, v174
	v_exp_f32_e32 v13, v13
	v_fmac_f32_e32 v172, 0x3f317217, v174
	v_min_f32_e32 v0, 0, v0
	v_cmp_lt_f32_e64 s[38:39], |v174|, s27
	v_mul_f32_e32 v2, 0x3f317217, v12
	v_and_b32_e32 v177, 0xffff0000, v116
	v_fma_f32 v2, v12, s31, -v2
	ds_write_b16 v104, v94 offset:30720
	v_fmac_f32_e32 v2, 0x3377d1cf, v12
	ds_write_b16_d16_hi v104, v94 offset:30760
	v_fmac_f32_e32 v2, 0x3f317217, v12
	ds_write_b16 v104, v95 offset:30800
	v_cmp_lt_f32_e64 s[16:17], |v12|, s27
	ds_write_b16_d16_hi v104, v95 offset:30840
	v_and_b32_e32 v15, 0xffff0000, v118
	v_cndmask_b32_e64 v172, v174, v172, s[38:39]
	v_cndmask_b32_e64 v2, v12, v2, s[16:17]
	v_cndmask_b32_e64 v174, 0, v157, s[36:37]
	v_cndmask_b32_e32 v12, 0, v157, vcc
	v_sub_f32_e32 v172, v172, v174
	v_sub_f32_e32 v2, v2, v12
	v_add_f32_e32 v174, 1.0, v175
	v_add_f32_e32 v12, 1.0, v13
	v_cmp_gt_f32_e64 s[36:37], s26, v174
	v_cmp_gt_f32_e32 vcc, s26, v12
	v_sub_f32_e32 v171, v171, v172
	v_sub_f32_e32 v1, v1, v2
	v_mul_f32_e32 v172, 0x3d800000, v171
; __device__ __forceinline__ unsigned pk2(float lo, float hi) { f32x2_t v = {lo, hi}; bf16x2_t b = __builtin_convertvector(v, bf16x2_t); return __builtin_bit_cast(unsigned, b); }
; __device__ __forceinline__ bf16_t f2bf(float f) { return (bf16_t)(pk2(f, 0.f) & 0xffffu); }
; __device__ __forceinline__ float lo_bf(unsigned u) { return __uint_as_float(u << 16); }
; __device__ __forceinline__ float hi_bf(unsigned u) { return __uint_as_float(u & 0xffff0000u); }
; __device__ __forceinline__ float sigmoidf_(float x) { return __builtin_amdgcn_rcpf(1.f + __expf(-x)); }
; __device__ __forceinline__ float siluf_(float x) { return x * __builtin_amdgcn_rcpf(1.f + __expf(-x)); }
; template <int MODE>
; __device__ void scan_unit(int swave, const Params& p, int j, int b, int h, int dir, char* shm) {
;     ...
;         g0 = (fminf(z0, 0.f) - __logf(1.f + __expf(-fabsf(z0)))) * (1.f / 16.f);
;         g1 = (fminf(z1, 0.f) - __logf(1.f + __expf(-fabsf(z1)))) * (1.f / 16.f);
;       } else {
;         const float f0 = lbv0 + (1.f - lbv0) * sigmoidf_(lo_bf(R.k)), f1 = lbv1 + (1.f - lbv1) * sigmoidf_(hi_bf(R.k));
;         g0 = __logf(fmaxf(f0, 1e-20f)); g1 = __logf(fmaxf(f1, 1e-20f));
;       }
;       float s0, s1;
;       const float cum0 = row_scan(g0, s0), cum1 = row_scan(g1, s1);
;       float q0, q1, k0, k1;
;       if (MODE == 0) { q0 = lo_bf(R.q); q1 = hi_bf(R.q); k0 = lo_bf(R.k) * 0.125f; k1 = hi_bf(R.k) * 0.125f; }
;       else { q0 = siluf_(lo_bf(R.q)); q1 = siluf_(hi_bf(R.q)); k0 = (1.f - lbv0) * sigmoidf_(-lo_bf(R.k)); k1 = (1.f - lbv1) * sigmoidf_(-hi_bf(R.k)); }
;       *(unsigned*)(qin + ti * QS + dp) = pk2(q0 * __expf(cum0), q1 * __expf(cum1));
;       *(unsigned*)(ktil + ti * QS + dp) = pk2(k0 * __expf(-cum0), k1 * __expf(-cum1));
;       koutT[dp * 16 + ti] = f2bf(k0 * __expf(s0 - cum0));
;       koutT[(dp + 1) * 16 + ti] = f2bf(k1 * __expf(s1 - cum1));
;       if (ti == 0) *(float2*)(dec + dp) = make_float2(__expf(s0), __expf(s1));
;       const unsigned v0 = R.v.x, v1 = R.v.y; const int c4 = vg * 4;
;       vT[(c4 + 0) * VS + ti] = (bf16_t)(v0 & 0xffff); vT[(c4 + 1) * VS + ti] = (bf16_t)(v0 >> 16);
;       vT[(c4 + 2) * VS + ti] = (bf16_t)(v1 & 0xffff); vT[(c4 + 3) * VS + ti] = (bf16_t)(v1 >> 16);
	v_mul_f32_e32 v2, 0x3d800000, v1
	v_cndmask_b32_e64 v175, 0, 32, s[36:37]
	v_cndmask_b32_e64 v13, 0, 32, vcc
	v_ldexp_f32 v174, v174, v175
	v_ldexp_f32 v12, v12, v13
	v_log_f32_e32 v174, v174
	v_log_f32_e32 v12, v12
	v_mul_f32_e32 v175, 0x3f317217, v174
	v_fma_f32 v175, v174, s31, -v175
	v_mul_f32_e32 v13, 0x3f317217, v12
	v_fmac_f32_e32 v175, 0x3377d1cf, v174
	v_fma_f32 v13, v12, s31, -v13
	v_fmac_f32_e32 v175, 0x3f317217, v174
	v_fmac_f32_e32 v13, 0x3377d1cf, v12
	v_cmp_lt_f32_e64 s[38:39], |v174|, s27
	v_fmac_f32_e32 v13, 0x3f317217, v12
	s_nop 0
	v_cndmask_b32_e64 v174, v174, v175, s[38:39]
	v_cmp_lt_f32_e64 s[16:17], |v12|, s27
	v_cndmask_b32_e64 v175, 0, v157, s[36:37]
	s_nop 0
	v_cndmask_b32_e64 v12, v12, v13, s[16:17]
	v_sub_f32_e32 v174, v174, v175
	v_cndmask_b32_e32 v13, 0, v157, vcc
	v_sub_f32_e32 v174, v170, v174
	v_sub_f32_e32 v12, v12, v13
	v_mul_f32_e32 v175, 0x3d800000, v174
	v_sub_f32_e32 v12, v0, v12
	v_mov_b32_dpp v170, v172 row_shr:1 row_mask:0xf bank_mask:0xf bound_ctrl:1
	v_mul_f32_e32 v13, 0x3d800000, v12
	v_fmac_f32_e32 v170, 0x3d800000, v171
	v_mov_b32_dpp v0, v2 row_shr:1 row_mask:0xf bank_mask:0xf bound_ctrl:1
	v_mov_b32_dpp v171, v175 row_shr:1 row_mask:0xf bank_mask:0xf bound_ctrl:1
	v_fmac_f32_e32 v0, 0x3d800000, v1
	v_fmac_f32_e32 v171, 0x3d800000, v174
	v_mov_b32_dpp v1, v13 row_shr:1 row_mask:0xf bank_mask:0xf bound_ctrl:1
	v_add_f32_dpp v170, v170, v170 row_shr:2 row_mask:0xf bank_mask:0xf bound_ctrl:1
	v_fmac_f32_e32 v1, 0x3d800000, v12
	v_lshlrev_b32_e32 v174, 16, v117
	v_add_f32_dpp v0, v0, v0 row_shr:2 row_mask:0xf bank_mask:0xf bound_ctrl:1
	v_add_f32_dpp v171, v171, v171 row_shr:2 row_mask:0xf bank_mask:0xf bound_ctrl:1
	v_lshlrev_b32_e32 v12, 16, v119
	v_add_f32_dpp v170, v170, v170 row_shr:4 row_mask:0xf bank_mask:0xf bound_ctrl:1
	v_add_f32_dpp v1, v1, v1 row_shr:2 row_mask:0xf bank_mask:0xf bound_ctrl:1
	v_and_b32_e32 v175, 0xffff0000, v117
	v_add_f32_dpp v171, v171, v171 row_shr:4 row_mask:0xf bank_mask:0xf bound_ctrl:1
	v_add_f32_dpp v0, v0, v0 row_shr:4 row_mask:0xf bank_mask:0xf bound_ctrl:1
	v_add_f32_dpp v172, v170, v170 row_shr:8 row_mask:0xf bank_mask:0xf bound_ctrl:1
	v_and_b32_e32 v13, 0xffff0000, v119
	v_mul_f32_e32 v178, 0x3fb8aa3b, v172
	v_add_f32_dpp v1, v1, v1 row_shr:4 row_mask:0xf bank_mask:0xf bound_ctrl:1
	v_add_f32_dpp v182, v171, v171 row_shr:8 row_mask:0xf bank_mask:0xf bound_ctrl:1
	v_add_f32_dpp v2, v0, v0 row_shr:8 row_mask:0xf bank_mask:0xf bound_ctrl:1
	v_mul_f32_e32 v179, 0x3fb8aa3b, v182
	v_mul_f32_e32 v16, 0x3fb8aa3b, v2
	v_exp_f32_e32 v178, v178
	v_add_f32_dpp v124, v1, v1 row_shr:8 row_mask:0xf bank_mask:0xf bound_ctrl:1
	v_exp_f32_e32 v179, v179
	v_mul_f32_e32 v17, 0x3fb8aa3b, v124
	ds_bpermute_b32 v170, v100, v172
	v_exp_f32_e32 v16, v16
	v_mul_f32_e32 v180, 0xbfb8aa3b, v172
	v_exp_f32_e32 v17, v17
	v_mul_f32_e32 v181, 0xbfb8aa3b, v182
	ds_bpermute_b32 v0, v100, v2
	v_exp_f32_e32 v180, v180
	v_mul_f32_e32 v18, 0xbfb8aa3b, v2
	v_exp_f32_e32 v181, v181
	v_mul_f32_e32 v19, 0xbfb8aa3b, v124
	ds_bpermute_b32 v171, v100, v182
	v_exp_f32_e32 v18, v18
	v_pk_mul_f32 v[174:175], v[178:179], v[174:175]
	v_exp_f32_e32 v19, v19
	s_mov_b32 s38, 0x3e000000
	ds_bpermute_b32 v1, v100, v124
	v_cvt_pk_bf16_f32 v178, v174, v175
	v_pk_mul_f32 v[12:13], v[16:17], v[12:13]
	v_pk_mul_f32 v[174:175], v[176:177], s[38:39] op_sel_hi:[1, 0]
	s_mov_b32 s16, 0x3e000000
	s_waitcnt lgkmcnt(3)
	v_sub_f32_e32 v172, v170, v172
	v_cvt_pk_bf16_f32 v16, v12, v13
	v_pk_mul_f32 v[176:177], v[174:175], v[180:181]
	v_mul_f32_e32 v172, 0x3fb8aa3b, v172
	v_pk_mul_f32 v[12:13], v[14:15], s[16:17] op_sel_hi:[1,0]
	v_cvt_pk_bf16_f32 v176, v176, v177
	s_waitcnt lgkmcnt(2)
	v_sub_f32_e32 v2, v0, v2
	ds_write2st64_b32 v101, v178, v176 offset0:141 offset1:150
	v_pk_mul_f32 v[14:15], v[12:13], v[18:19]
	v_exp_f32_e32 v172, v172
	v_mul_f32_e32 v2, 0x3fb8aa3b, v2
	s_waitcnt lgkmcnt(2)
	v_sub_f32_e32 v176, v171, v182
	v_cvt_pk_bf16_f32 v14, v14, v15
	v_mul_f32_e32 v176, 0x3fb8aa3b, v176
	ds_write2st64_b32 v101, v16, v14 offset0:94 offset1:103
	v_exp_f32_e32 v176, v176
	v_exp_f32_e32 v2, v2
	v_mul_f32_e32 v172, v174, v172
	s_waitcnt lgkmcnt(2)
	v_sub_f32_e32 v14, v1, v124
	v_cvt_pk_bf16_f32 v172, v172, s0
	v_mul_f32_e32 v14, 0x3fb8aa3b, v14
	ds_write_b16 v102, v172 offset:40704
	v_exp_f32_e32 v14, v14
	v_mul_f32_e32 v172, v175, v176
	v_mul_f32_e32 v2, v12, v2
	v_cvt_pk_bf16_f32 v172, v172, s0
	v_cvt_pk_bf16_f32 v2, v2, s0
	ds_write_b16 v102, v172 offset:40736
	ds_write_b16 v102, v2 offset:28672
	s_and_saveexec_b64 s[38:39], s[14:15]
	s_cbranch_execz .LBB0_686
	v_mul_f32_e32 v171, 0x3fb8aa3b, v171
	v_mul_f32_e32 v170, 0x3fb8aa3b, v170
	v_exp_f32_e32 v171, v171
	v_exp_f32_e32 v170, v170
	ds_write_b64 v103, v[170:171] offset:47872
.LBB0_686:
	s_or_b64 exec, exec, s[38:39]
	v_mul_f32_e32 v2, v13, v14
	ds_write_b16 v104, v90 offset:42752
	v_cvt_pk_bf16_f32 v2, v2, s0
	ds_write_b16_d16_hi v104, v90 offset:42792
	ds_write_b16 v102, v2 offset:28704
	ds_write_b16 v104, v91 offset:42832
	s_and_saveexec_b64 s[16:17], s[14:15]
	s_cbranch_execz .LBB0_684
	v_mul_f32_e32 v1, 0x3fb8aa3b, v1
	v_mul_f32_e32 v0, 0x3fb8aa3b, v0
	v_exp_f32_e32 v1, v1
	v_exp_f32_e32 v0, v0
	ds_write_b64 v103, v[0:1] offset:35840
; template <int MODE>
; __device__ void scan_unit(int swave, const Params& p, int j, int b, int h, int dir, char* shm) {
;     ...
;   auto compute = [&](const char* buf, bf16_t* obuf) {
;     const bf16_t* qin = (const bf16_t*)buf; const bf16_t* ktil = (const bf16_t*)(buf + OFF_KT); const bf16_t* koutT = (const bf16_t*)(buf + OFF_KO);
;     const bf16_t* vT = (const bf16_t*)(buf + OFF_VT); const float* dec = (const float*)(buf + OFF_DEC);
;     bf16x8 Asc = {0, 0, 0, 0, 0, 0, 0, 0};
;     if (KS == 1 || wk == 0) {
;       f32x4 sc = {0.f, 0.f, 0.f, 0.f};
; #pragma unroll
;       for (int m = 0; m < DK / 32; ++m) {
;         const bf16x8 a = *(const bf16x8*)(ktil + r * QS + m * 32 + q4 * 8);
;         const bf16x8 bb = *(const bf16x8*)(qin + r * QS + m * 32 + q4 * 8);
;         sc = __builtin_amdgcn_mfma_f32_16x16x32_bf16(a, bb, sc, 0, 0, 0);
;       }
;       {
;         const unsigned p01 = pk2(q4 * 4 + 0 > r ? 0.f : sc[0], q4 * 4 + 1 > r ? 0.f : sc[1]);
;         const unsigned p23 = pk2(q4 * 4 + 2 > r ? 0.f : sc[2], q4 * 4 + 3 > r ? 0.f : sc[3]);
;         Asc[0] = (short)(p01 & 0xffff); Asc[1] = (short)(p01 >> 16); Asc[2] = (short)(p23 & 0xffff); Asc[3] = (short)(p23 >> 16);
;       }
;     }
;     bf16x8 Bv[NVT];
; #pragma unroll
;     for (int t = 0; t < NVT; ++t) {
;       const uint2 vv = *(const uint2*)(vT + ((vt0 + t) * 16 + r) * VS + q4 * 4);
;       Bv[t] = (bf16x8){(short)(vv.x & 0xffff), (short)(vv.x >> 16), (short)(vv.y & 0xffff), (short)(vv.y >> 16), 0, 0, 0, 0};
;     }
;     bf16x8 Aq[2];
; #pragma unroll
;     for (int m = 0; m < 2; ++m) {
;       const uint2 lo = *(const uint2*)(qin + r * QS + slab + (2 * m) * 16 + q4 * 4);
;       const uint2 hi = *(const uint2*)(qin + r * QS + slab + (2 * m + 1) * 16 + q4 * 4);
;       Aq[m] = (bf16x8){(short)(lo.x & 0xffff), (short)(lo.x >> 16), (short)(lo.y & 0xffff), (short)(lo.y >> 16),
;                        (short)(hi.x & 0xffff), (short)(hi.x >> 16), (short)(hi.y & 0xffff), (short)(hi.y >> 16)};
;     }
;     f32x4 o[NVT];
; #pragma unroll
;     for (int t = 0; t < NVT; ++t) {
;       o[t] = (f32x4){0.f, 0.f, 0.f, 0.f};
;       if (KS == 1 || wk == 0) o[t] = __builtin_amdgcn_mfma_f32_16x16x32_bf16(Asc, Bv[t], o[t], 0, 0, 0);
;     }
; #pragma unroll
;     for (int m = 0; m < 2; ++m)
; #pragma unroll
;       for (int t = 0; t < NVT; ++t) {
;         const f32x4 s0 = S[2 * m][t], s1 = S[2 * m + 1][t];
.LBB0_684:
	s_or_b64 exec, exec, s[16:17]
	ds_write_b16_d16_hi v104, v91 offset:42872
	ds_read_b128 v[4:7], v108 offset:2304
	ds_read_b128 v[8:11], v108
	ds_read_b128 v[12:15], v108 offset:2368
	ds_read_b128 v[16:19], v108 offset:64
	v_mov_b32_e32 v2, v3
	v_mov_b32_e32 v128, v3
	s_waitcnt lgkmcnt(2)
	v_mfma_f32_16x16x32_bf16 v[4:7], v[4:7], v[8:11], 0
	ds_read_b64 v[8:9], v109 offset:6656
	ds_read2_b64 v[116:119], v115 offset1:4
	ds_read2_b64 v[124:127], v115 offset0:8 offset1:12
	v_mov_b32_e32 v10, v3
	v_mov_b32_e32 v11, v3
	s_waitcnt lgkmcnt(3)
	v_mfma_f32_16x16x32_bf16 v[4:7], v[12:15], v[16:19], v[4:7]
	s_waitcnt lgkmcnt(1)
	v_bfi_b32 v118, s30, v118, v118
	s_waitcnt lgkmcnt(0)
	v_bfi_b32 v126, s30, v126, v126
	v_cvt_pk_bf16_f32 v12, v48, v49
	v_cvt_pk_bf16_f32 v13, v50, v51
	v_cvt_pk_bf16_f32 v14, v44, v45
	s_nop 0
	v_cndmask_b32_e64 v0, v4, 0, s[6:7]
	v_cndmask_b32_e64 v1, 0, v5, s[8:9]
	v_cndmask_b32_e64 v4, v6, 0, s[10:11]
	v_cndmask_b32_e64 v5, v7, 0, s[12:13]
	v_cvt_pk_bf16_f32 v0, v0, v1
	v_cvt_pk_bf16_f32 v1, v4, v5
	v_cvt_pk_bf16_f32 v15, v46, v47
	v_mov_b32_e32 v129, v3
	v_mfma_f32_16x16x32_bf16 v[4:7], v[0:3], v[8:11], 0
	v_mfma_f32_16x16x32_bf16 v[4:7], v[116:119], v[12:15], v[4:7]
	v_cvt_pk_bf16_f32 v12, v40, v41
	v_cvt_pk_bf16_f32 v13, v42, v43
	v_cvt_pk_bf16_f32 v14, v36, v37
	v_cvt_pk_bf16_f32 v15, v38, v39
	s_nop 1
	v_mfma_f32_16x16x32_bf16 v[4:7], v[124:127], v[12:15], v[4:7]
	v_add_u32_e32 v124, 0x100, v111
	s_nop 6
	v_cvt_pk_bf16_f32 v0, v4, s0
	v_cvt_pk_bf16_f32 v1, v5, s0
	ds_write_b16 v110, v0 offset:48128
	ds_write_b16 v110, v1 offset:48392
	v_cvt_pk_bf16_f32 v0, v6, s0
	ds_write_b16 v110, v0 offset:48656
	v_cvt_pk_bf16_f32 v0, v7, s0
	ds_write_b16 v110, v0 offset:48920
	ds_read2st64_b64 v[4:7], v111 offset0:9 offset1:10
	ds_read2st64_b64 v[12:15], v111 offset0:11 offset1:12
	ds_read_b128 v[16:19], v112 offset:11776
	ds_read_b128 v[116:119], v112 offset:11840
	s_waitcnt lgkmcnt(3)
	v_mov_b32_e32 v0, v4
	v_mov_b32_e32 v1, v5
	s_waitcnt lgkmcnt(1)
	v_pk_mul_f32 v[18:19], v[50:51], v[18:19]
	v_pk_mul_f32 v[16:17], v[48:49], v[16:17]
	s_waitcnt lgkmcnt(0)
	v_pk_mul_f32 v[4:5], v[44:45], v[116:117]
	ds_read_b128 v[48:51], v112 offset:11968
	v_mfma_f32_16x16x16_bf16 v[16:19], v[0:1], v[8:9], v[16:19]
	v_mov_b32_e32 v0, v6
	v_mov_b32_e32 v1, v7
	v_pk_mul_f32 v[6:7], v[46:47], v[118:119]
	ds_read_b128 v[44:47], v112 offset:11904
	s_waitcnt lgkmcnt(0)
	v_pk_mul_f32 v[42:43], v[42:43], v[46:47]
	v_mfma_f32_16x16x16_bf16 v[4:7], v[0:1], v[8:9], v[4:7]
	v_pk_mul_f32 v[40:41], v[40:41], v[44:45]
	s_nop 1
	v_mfma_f32_16x16x16_bf16 v[116:119], v[12:13], v[8:9], v[40:43]
	v_mov_b32_e32 v0, v14
	v_mov_b32_e32 v1, v15
	ds_read_b128 v[12:15], v108 offset:14336
	v_pk_mul_f32 v[38:39], v[38:39], v[50:51]
	v_pk_mul_f32 v[36:37], v[36:37], v[48:49]
	s_nop 1
	v_mfma_f32_16x16x16_bf16 v[8:11], v[0:1], v[8:9], v[36:39]
	s_nop 2
	ds_read_b128 v[36:39], v108 offset:14400
	ds_read_b128 v[40:43], v108 offset:12032
	ds_read_b128 v[44:47], v108 offset:12096
	s_waitcnt lgkmcnt(1)
	v_mfma_f32_16x16x32_bf16 v[12:15], v[12:15], v[40:43], 0
	s_waitcnt lgkmcnt(0)
	v_mfma_f32_16x16x32_bf16 v[12:15], v[36:39], v[44:47], v[12:15]
	v_add_u32_e32 v36, 0x2800, v115
	v_cvt_pk_bf16_f32 v44, v16, v17
	v_cvt_pk_bf16_f32 v45, v18, v19
	v_cvt_pk_bf16_f32 v46, v4, v5
	v_cvt_pk_bf16_f32 v47, v6, v7
	s_nop 2
	v_cndmask_b32_e64 v0, v12, 0, s[6:7]
	v_cndmask_b32_e64 v1, 0, v13, s[8:9]
	v_cvt_pk_bf16_f32 v0, v0, v1
	v_cndmask_b32_e64 v1, v14, 0, s[10:11]
	v_cndmask_b32_e64 v2, v15, 0, s[12:13]
	ds_read2_b64 v[12:15], v36 offset0:224 offset1:228
	ds_read2_b64 v[36:39], v36 offset0:232 offset1:236
	v_cvt_pk_bf16_f32 v1, v1, v2
	ds_read_b64 v[126:127], v109 offset:18688
	v_mov_b32_e32 v2, v3
	s_waitcnt lgkmcnt(2)
	v_bfi_b32 v14, s30, v14, v14
	s_waitcnt lgkmcnt(1)
	v_bfi_b32 v38, s30, v38, v38
	s_waitcnt lgkmcnt(0)
	v_mfma_f32_16x16x32_bf16 v[40:43], v[0:3], v[126:129], 0
	v_mfma_f32_16x16x32_bf16 v[12:15], v[12:15], v[44:47], v[40:43]
	s_nop 6
	v_cvt_pk_bf16_f32 v40, v116, v117
	v_cvt_pk_bf16_f32 v41, v118, v119
	v_cvt_pk_bf16_f32 v42, v8, v9
	v_cvt_pk_bf16_f32 v43, v10, v11
	s_nop 1
	v_mfma_f32_16x16x32_bf16 v[12:15], v[36:39], v[40:43], v[12:15]
	s_nop 7
	v_cvt_pk_bf16_f32 v0, v12, s0
	ds_write_b16 v110, v0 offset:52352
	v_cvt_pk_bf16_f32 v0, v13, s0
	ds_write_b16 v110, v0 offset:52616
	v_cvt_pk_bf16_f32 v0, v14, s0
	ds_write_b16 v110, v0 offset:52880
	v_cvt_pk_bf16_f32 v0, v15, s0
	ds_write_b16 v110, v0 offset:53144
	ds_read2st64_b64 v[12:15], v124 offset0:32 offset1:33
	ds_read2st64_b64 v[36:39], v124 offset0:34 offset1:35
	ds_read_b128 v[40:43], v112 offset:23808
	ds_read_b128 v[44:47], v112 offset:23872
	s_waitcnt lgkmcnt(3)
	s_waitcnt lgkmcnt(1)
	v_pk_mul_f32 v[18:19], v[18:19], v[42:43]
	v_pk_mul_f32 v[16:17], v[16:17], v[40:41]
	s_waitcnt lgkmcnt(0)
	v_pk_mul_f32 v[6:7], v[6:7], v[46:47]
	v_pk_mul_f32 v[4:5], v[4:5], v[44:45]
	v_mfma_f32_16x16x16_bf16 v[40:43], v[12:13], v[126:127], v[16:19]
	v_mov_b32_e32 v0, v14
	v_mov_b32_e32 v1, v15
	ds_read_b128 v[12:15], v112 offset:24000
	s_nop 0
	v_mfma_f32_16x16x16_bf16 v[44:47], v[0:1], v[126:127], v[4:7]
	s_nop 1
	ds_read_b128 v[4:7], v112 offset:23936
	s_waitcnt lgkmcnt(0)
	s_barrier
; __device__ __forceinline__ unsigned pk2(float lo, float hi) { f32x2_t v = {lo, hi}; bf16x2_t b = __builtin_convertvector(v, bf16x2_t); return __builtin_bit_cast(unsigned, b); }
; __device__ __forceinline__ float lo_bf(unsigned u) { return __uint_as_float(u << 16); }
; __device__ __forceinline__ float hi_bf(unsigned u) { return __uint_as_float(u & 0xffff0000u); }
; template <int MODE>
; __device__ void scan_unit(int swave, const Params& p, int j, int b, int h, int dir, char* shm) {
;     ...
;   auto ostore = [&](int c, const bf16_t* obuf) {
;     for (int idx = tid; idx < 16 * DV / 4; idx += 512) {
;       const int i = idx / (DV / 4), cc = (idx % (DV / 4)) * 4;
;       uint2 o = *(const uint2*)(obuf + i * OS + cc);
;       if (KS == 2) {
;         const uint2 o2 = *(const uint2*)(obuf + (16 + i) * OS + cc);
;         o.x = pk2(lo_bf(o.x) + lo_bf(o2.x), hi_bf(o.x) + hi_bf(o2.x)); o.y = pk2(lo_bf(o.y) + lo_bf(o2.y), hi_bf(o.y) + hi_bf(o2.y));
;       }
;       *(uint2*)(O + (rowbase + tokof(c, i)) * OLD + cc) = o;
;     }
;     ...
;   auto body = [&](int it, Raw& c0, Raw& c1, Raw& n0, Raw& n1) {
;     touch(c0); touch(c1);
;     __builtin_amdgcn_sched_barrier(0);
;     const int cA = 2 * it + 4 < NCH ? 2 * it + 4 : NCH - 2;
;     load_raw(cA, n0); load_raw(cA + 1, n1);
;     if (it > 0) { ostore(2 * it - 2, obp((it - 1) & 1, 0)); ostore(2 * it - 1, obp((it - 1) & 1, 1)); }
;     stage2(c0, bufp((it + 1) & 1, 0), 0); stage2(c1, bufp((it + 1) & 1, 1), 0);
	s_waitcnt lgkmcnt(0)
	v_pk_mul_f32 v[6:7], v[118:119], v[6:7]
	v_pk_mul_f32 v[4:5], v[116:117], v[4:5]
	s_nop 1
	v_mfma_f32_16x16x16_bf16 v[48:51], v[36:37], v[126:127], v[4:7]
	v_mov_b32_e32 v0, v38
	v_mov_b32_e32 v1, v39
	s_nop 0
	v_pk_mul_f32 v[6:7], v[10:11], v[14:15]
	v_pk_mul_f32 v[4:5], v[8:9], v[12:13]
	s_nop 1
	v_mfma_f32_16x16x16_bf16 v[36:39], v[0:1], v[126:127], v[4:7]
	s_add_i32 s16, s28, 0x60
	s_and_b64 s[2:3], s[2:3], exec
	s_cselect_b32 s2, s16, 0x7e0
	v_or_b32_e32 v2, s2, v99
	v_sub_u32_e32 v0, 0x7ff, v2
	v_cndmask_b32_e64 v0, v0, v2, s[0:1]
	v_ashrrev_i32_e32 v1, 31, v0
	v_lshl_add_u64 v[0:1], s[18:19], 0, v[0:1]
	v_mov_b64_e32 v[4:5], s[46:47]
	v_mad_u64_u32 v[6:7], s[2:3], v0, s53, v[4:5]
	v_mad_i32_i24 v7, v1, s53, v7
	v_lshl_add_u64 v[0:1], v[6:7], 0, s[94:95]
	v_lshl_add_u64 v[0:1], v[0:1], 0, v[82:83]
	s_mov_b32 s45, s95
	s_mov_b32 s51, s95
	v_lshl_add_u64 v[8:9], v[6:7], 0, s[44:45]
	global_load_dword v119, v[0:1], off
	global_load_dword v118, v[0:1], off offset:512
	global_load_dwordx4 v[16:19], v[8:9], off
	v_lshl_add_u64 v[0:1], v[6:7], 0, s[50:51]
	v_lshl_add_u64 v[0:1], v[0:1], 0, v[84:85]
	global_load_dwordx4 v[12:15], v[8:9], off offset:16
	global_load_dwordx2 v[94:95], v[0:1], off offset:1024
	v_or_b32_e32 v0, 16, v2
	v_sub_u32_e32 v1, 0x7ff, v0
	v_cndmask_b32_e64 v0, v1, v0, s[0:1]
	v_ashrrev_i32_e32 v1, 31, v0
	v_lshl_add_u64 v[0:1], s[18:19], 0, v[0:1]
	v_mad_u64_u32 v[4:5], s[2:3], v0, s53, v[4:5]
	v_mad_i32_i24 v5, v1, s53, v5
	v_lshl_add_u64 v[0:1], v[4:5], 0, s[94:95]
	v_lshl_add_u64 v[0:1], v[0:1], 0, v[82:83]
	v_lshl_add_u64 v[6:7], v[4:5], 0, s[44:45]
	global_load_dword v117, v[0:1], off
	global_load_dword v116, v[0:1], off offset:512
	global_load_dwordx4 v[8:11], v[6:7], off
	v_lshl_add_u64 v[0:1], v[4:5], 0, s[50:51]
	v_lshl_add_u64 v[0:1], v[0:1], 0, v[84:85]
	global_load_dwordx4 v[4:7], v[6:7], off offset:16
	s_nop 0
	global_load_dwordx2 v[90:91], v[0:1], off offset:1024
	s_and_saveexec_b64 s[2:3], s[4:5]
	s_cbranch_execz .LBB0_691
	s_sub_i32 vcc_lo, 0x7e0, s28
	s_cmp_lg_u64 s[0:1], 0
	s_cselect_b32 vcc_lo, s28, vcc_lo
	s_add_i32 vcc_lo, vcc_lo, s18
	s_lshl_b32 vcc_lo, vcc_lo, 11
	s_add_u32 s16, s48, vcc_lo
	s_addc_u32 s17, s49, 0
	v_add_u32_e32 v160, v113, v166
	v_add_u32_e32 v161, v114, v166
	ds_read_b64 v[162:163], v160
	ds_read_b64 v[164:165], v161
	s_waitcnt lgkmcnt(1)
	global_store_dwordx2 v167, v[162:163], s[16:17]
	s_waitcnt lgkmcnt(0)
	global_store_dwordx2 v168, v[164:165], s[16:17]
	s_or_b64 exec, exec, s[2:3]
	s_waitcnt vmcnt(12)
	s_branch .Llw_join_677b

; __device__ __forceinline__ float lo_bf(unsigned u) { return __uint_as_float(u << 16); }
; __device__ __forceinline__ float hi_bf(unsigned u) { return __uint_as_float(u & 0xffff0000u); }
; template <int MODE>
; __device__ void scan_unit(int swave, const Params& p, int j, int b, int h, int dir, char* shm) {
;     ...
;       if (MODE == 0) {
;         float z0 = bav0, z1 = bav1;
;         const unsigned lw[8] = {R.lr0.x, R.lr0.y, R.lr0.z, R.lr0.w, R.lr1.x, R.lr1.y, R.lr1.z, R.lr1.w};
; #pragma unroll
;         for (int e = 0; e < 8; ++e) {
;           const float a0 = lo_bf(lw[e]), a1 = hi_bf(lw[e]);
;           z0 += a0 * wa2r[4 * e] + a1 * wa2r[4 * e + 2];
;           z1 += a0 * wa2r[4 * e + 1] + a1 * wa2r[4 * e + 3];
;         }
;         g0 = (fminf(z0, 0.f) - __logf(1.f + __expf(-fabsf(z0)))) * (1.f / 16.f);
;         g1 = (fminf(z1, 0.f) - __logf(1.f + __expf(-fabsf(z1)))) * (1.f / 16.f);
.Llw_join_677b:
	v_and_b32_e32 v171, 0xffff0000, v24
	v_and_b32_e32 v1, 0xffff0000, v32
	v_lshlrev_b32_e32 v170, 16, v24
	v_lshlrev_b32_e32 v0, 16, v32
	v_mul_f32_e32 v172, v54, v171
	v_mul_f32_e32 v2, v54, v1
	v_mul_f32_e32 v171, v55, v171
	v_mul_f32_e32 v1, v55, v1
	v_fmac_f32_e32 v171, v53, v170
	v_fmac_f32_e32 v1, v53, v0
	v_and_b32_e32 v178, 0xffff0000, v25
	v_and_b32_e32 v32, 0xffff0000, v33
	v_fmac_f32_e32 v172, v52, v170
	v_fmac_f32_e32 v2, v52, v0
	v_add_f32_e32 v170, v81, v171
	v_add_f32_e32 v0, v81, v1
	v_lshlrev_b32_e32 v171, 16, v25
	v_lshlrev_b32_e32 v1, 16, v33
	v_mul_f32_e32 v179, v58, v178
	v_mul_f32_e32 v33, v58, v32
	v_mul_f32_e32 v178, v59, v178
	v_mul_f32_e32 v32, v59, v32
	v_fmac_f32_e32 v178, v57, v171
	v_fmac_f32_e32 v32, v57, v1
	v_add_f32_e32 v172, v80, v172
	v_add_f32_e32 v2, v80, v2
	v_fmac_f32_e32 v179, v56, v171
	v_fmac_f32_e32 v33, v56, v1
	v_add_f32_e32 v170, v170, v178
	v_add_f32_e32 v0, v0, v32
	v_and_b32_e32 v178, 0xffff0000, v26
	v_and_b32_e32 v32, 0xffff0000, v34
	v_add_f32_e32 v172, v172, v179
	v_add_f32_e32 v2, v2, v33
	v_lshlrev_b32_e32 v171, 16, v26
	v_lshlrev_b32_e32 v1, 16, v34
	v_mul_f32_e32 v179, v68, v178
	v_mul_f32_e32 v33, v68, v32
	v_mul_f32_e32 v178, v69, v178
	v_mul_f32_e32 v32, v69, v32
	v_fmac_f32_e32 v178, v77, v171
	v_fmac_f32_e32 v32, v77, v1
	v_fmac_f32_e32 v179, v76, v171
	v_fmac_f32_e32 v33, v76, v1
	v_add_f32_e32 v170, v170, v178
	v_add_f32_e32 v0, v0, v32
	v_and_b32_e32 v178, 0xffff0000, v27
	v_and_b32_e32 v32, 0xffff0000, v35
	v_add_f32_e32 v172, v172, v179
	v_add_f32_e32 v2, v2, v33
	v_lshlrev_b32_e32 v171, 16, v27
	v_lshlrev_b32_e32 v1, 16, v35
	v_mul_f32_e32 v179, v72, v178
	v_mul_f32_e32 v33, v72, v32
	v_mul_f32_e32 v178, v73, v178
	v_mul_f32_e32 v32, v73, v32
	v_fmac_f32_e32 v179, v70, v171
	v_fmac_f32_e32 v33, v70, v1
	v_fmac_f32_e32 v178, v71, v171
	v_fmac_f32_e32 v32, v71, v1
	v_lshlrev_b32_e32 v171, 16, v20
	v_lshlrev_b32_e32 v1, 16, v28
	v_and_b32_e32 v174, 0xffff0000, v20
	v_and_b32_e32 v28, 0xffff0000, v28
	v_add_f32_e32 v170, v170, v178
	v_add_f32_e32 v0, v0, v32
	v_mul_f32_e32 v178, v62, v174
	v_mul_f32_e32 v32, v62, v28
	v_mul_f32_e32 v174, v63, v174
	v_mul_f32_e32 v28, v63, v28
	v_add_f32_e32 v172, v172, v179
	v_fmac_f32_e32 v178, v60, v171
	v_add_f32_e32 v2, v2, v33
	v_fmac_f32_e32 v174, v61, v171
	v_fmac_f32_e32 v32, v60, v1
	v_and_b32_e32 v171, 0xffff0000, v21
	v_fmac_f32_e32 v28, v61, v1
	v_add_f32_e32 v172, v172, v178
	v_and_b32_e32 v1, 0xffff0000, v29
	v_add_f32_e32 v178, v170, v174
	v_add_f32_e32 v2, v2, v32
	v_lshlrev_b32_e32 v170, 16, v21
	v_add_f32_e32 v32, v0, v28
	v_mul_f32_e32 v174, v66, v171
	v_lshlrev_b32_e32 v0, 16, v29
	v_fmac_f32_e32 v174, v64, v170
	v_mul_f32_e32 v28, v66, v1
	v_add_f32_e32 v172, v172, v174
	v_fmac_f32_e32 v28, v64, v0
	v_mul_f32_e32 v179, v67, v171
	v_add_f32_e32 v2, v2, v28
	v_and_b32_e32 v175, 0xffff0000, v23
	v_mul_f32_e32 v33, v67, v1
	v_and_b32_e32 v174, 0xffff0000, v22
	v_and_b32_e32 v29, 0xffff0000, v31
	v_fmac_f32_e32 v179, v65, v170
	v_and_b32_e32 v28, 0xffff0000, v30
	v_lshlrev_b32_e32 v171, 16, v23
	v_fmac_f32_e32 v33, v65, v0
	v_lshlrev_b32_e32 v170, 16, v22
	v_lshlrev_b32_e32 v1, 16, v31
	v_pk_mul_f32 v[176:177], v[78:79], v[174:175]
	v_lshlrev_b32_e32 v0, 16, v30
	v_pk_mul_f32 v[174:175], v[88:89], v[174:175]
	v_pk_mul_f32 v[30:31], v[78:79], v[28:29]
	v_pk_fma_f32 v[176:177], v[74:75], v[170:171], v[176:177]
	v_pk_mul_f32 v[28:29], v[88:89], v[28:29]
	v_pk_fma_f32 v[170:171], v[86:87], v[170:171], v[174:175]
	v_pk_fma_f32 v[30:31], v[74:75], v[0:1], v[30:31]
	v_add_f32_e32 v172, v172, v176
	v_pk_fma_f32 v[0:1], v[86:87], v[0:1], v[28:29]
	v_add_f32_e32 v172, v172, v177
	v_add_f32_e32 v2, v2, v30
	v_mul_f32_e64 v176, |v172|, s56
	v_add_f32_e32 v2, v2, v31
	v_exp_f32_e32 v176, v176
	v_mul_f32_e64 v30, |v2|, s56
	v_add_f32_e32 v177, v178, v179
	v_exp_f32_e32 v30, v30
	v_add_f32_e32 v170, v177, v170
	v_add_f32_e32 v31, v32, v33
	v_add_f32_e32 v170, v170, v171
	v_add_f32_e32 v0, v31, v0
	v_add_f32_e32 v174, 1.0, v176
	v_add_f32_e32 v0, v0, v1
	v_cmp_gt_f32_e64 s[36:37], s26, v174
	v_add_f32_e32 v28, 1.0, v30
	v_min_f32_e32 v171, 0, v172
	v_cmp_gt_f32_e32 vcc, s26, v28
	v_lshlrev_b32_e32 v176, 16, v120
	v_min_f32_e32 v1, 0, v2
	v_cndmask_b32_e64 v175, 0, 32, s[36:37]
	v_lshlrev_b32_e32 v30, 16, v122
	v_ldexp_f32 v174, v174, v175
	v_cndmask_b32_e64 v29, 0, 32, vcc
	v_log_f32_e32 v174, v174
	v_ldexp_f32 v28, v28, v29
	v_mul_f32_e64 v175, |v170|, s56
	v_log_f32_e32 v28, v28
	v_exp_f32_e32 v175, v175
	v_mul_f32_e64 v29, |v0|, s56
	v_min_f32_e32 v170, 0, v170
	v_mul_f32_e32 v172, 0x3f317217, v174
	v_exp_f32_e32 v29, v29
	v_fma_f32 v172, v174, s31, -v172
	v_min_f32_e32 v0, 0, v0
	v_fmac_f32_e32 v172, 0x3377d1cf, v174
	v_mul_f32_e32 v2, 0x3f317217, v28
	v_fmac_f32_e32 v172, 0x3f317217, v174
	v_fma_f32 v2, v28, s31, -v2
	v_cmp_lt_f32_e64 s[40:41], |v174|, s27
	v_fmac_f32_e32 v2, 0x3377d1cf, v28
	v_and_b32_e32 v177, 0xffff0000, v120
	v_fmac_f32_e32 v2, 0x3f317217, v28
	s_mov_b32 s38, 0x3e000000
	v_cmp_lt_f32_e64 s[16:17], |v28|, s27
	v_cndmask_b32_e64 v172, v174, v172, s[40:41]
	v_and_b32_e32 v31, 0xffff0000, v122
	v_cndmask_b32_e64 v174, 0, v157, s[36:37]
	s_mov_b32 s2, 0x3e000000
	v_sub_f32_e32 v172, v172, v174
	v_cndmask_b32_e64 v2, v28, v2, s[16:17]
	v_add_f32_e32 v174, 1.0, v175
	v_cndmask_b32_e32 v28, 0, v157, vcc
	v_cmp_gt_f32_e64 s[36:37], s26, v174
	v_sub_f32_e32 v2, v2, v28
; __device__ __forceinline__ unsigned pk2(float lo, float hi) { f32x2_t v = {lo, hi}; bf16x2_t b = __builtin_convertvector(v, bf16x2_t); return __builtin_bit_cast(unsigned, b); }
; __device__ __forceinline__ bf16_t f2bf(float f) { return (bf16_t)(pk2(f, 0.f) & 0xffffu); }
; __device__ __forceinline__ float lo_bf(unsigned u) { return __uint_as_float(u << 16); }
; __device__ __forceinline__ float hi_bf(unsigned u) { return __uint_as_float(u & 0xffff0000u); }
; __device__ __forceinline__ float sigmoidf_(float x) { return __builtin_amdgcn_rcpf(1.f + __expf(-x)); }
; __device__ __forceinline__ float siluf_(float x) { return x * __builtin_amdgcn_rcpf(1.f + __expf(-x)); }
; template <int MODE>
; __device__ void scan_unit(int swave, const Params& p, int j, int b, int h, int dir, char* shm) {
;     ...
;         g0 = (fminf(z0, 0.f) - __logf(1.f + __expf(-fabsf(z0)))) * (1.f / 16.f);
;         g1 = (fminf(z1, 0.f) - __logf(1.f + __expf(-fabsf(z1)))) * (1.f / 16.f);
;       } else {
;         const float f0 = lbv0 + (1.f - lbv0) * sigmoidf_(lo_bf(R.k)), f1 = lbv1 + (1.f - lbv1) * sigmoidf_(hi_bf(R.k));
;         g0 = __logf(fmaxf(f0, 1e-20f)); g1 = __logf(fmaxf(f1, 1e-20f));
;       }
;       float s0, s1;
;       const float cum0 = row_scan(g0, s0), cum1 = row_scan(g1, s1);
;       float q0, q1, k0, k1;
;       if (MODE == 0) { q0 = lo_bf(R.q); q1 = hi_bf(R.q); k0 = lo_bf(R.k) * 0.125f; k1 = hi_bf(R.k) * 0.125f; }
;       else { q0 = siluf_(lo_bf(R.q)); q1 = siluf_(hi_bf(R.q)); k0 = (1.f - lbv0) * sigmoidf_(-lo_bf(R.k)); k1 = (1.f - lbv1) * sigmoidf_(-hi_bf(R.k)); }
;       *(unsigned*)(qin + ti * QS + dp) = pk2(q0 * __expf(cum0), q1 * __expf(cum1));
;       *(unsigned*)(ktil + ti * QS + dp) = pk2(k0 * __expf(-cum0), k1 * __expf(-cum1));
;       koutT[dp * 16 + ti] = f2bf(k0 * __expf(s0 - cum0));
;       koutT[(dp + 1) * 16 + ti] = f2bf(k1 * __expf(s1 - cum1));
;       if (ti == 0) *(float2*)(dec + dp) = make_float2(__expf(s0), __expf(s1));
;       const unsigned v0 = R.v.x, v1 = R.v.y; const int c4 = vg * 4;
;       vT[(c4 + 0) * VS + ti] = (bf16_t)(v0 & 0xffff); vT[(c4 + 1) * VS + ti] = (bf16_t)(v0 >> 16);
;       vT[(c4 + 2) * VS + ti] = (bf16_t)(v1 & 0xffff); vT[(c4 + 3) * VS + ti] = (bf16_t)(v1 >> 16);
	v_sub_f32_e32 v171, v171, v172
	v_add_f32_e32 v28, 1.0, v29
	v_mul_f32_e32 v172, 0x3d800000, v171
	v_cmp_gt_f32_e32 vcc, s26, v28
	v_cndmask_b32_e64 v175, 0, 32, s[36:37]
	v_sub_f32_e32 v1, v1, v2
	v_ldexp_f32 v174, v174, v175
	v_mul_f32_e32 v2, 0x3d800000, v1
	v_log_f32_e32 v174, v174
	v_cndmask_b32_e64 v29, 0, 32, vcc
	ds_write_b16 v104, v96 offset:6656
	v_ldexp_f32 v28, v28, v29
	ds_write_b16_d16_hi v104, v96 offset:6696
	v_log_f32_e32 v28, v28
	ds_write_b16 v104, v97 offset:6736
	v_mul_f32_e32 v29, 0x3f317217, v28
	ds_write_b16_d16_hi v104, v97 offset:6776
	v_fma_f32 v29, v28, s31, -v29
	v_mul_f32_e32 v175, 0x3f317217, v174
	v_fmac_f32_e32 v29, 0x3377d1cf, v28
	v_fma_f32 v175, v174, s31, -v175
	v_fmac_f32_e32 v29, 0x3f317217, v28
	v_fmac_f32_e32 v175, 0x3377d1cf, v174
	v_cmp_lt_f32_e64 s[16:17], |v28|, s27
	v_fmac_f32_e32 v175, 0x3f317217, v174
	s_nop 0
	v_cndmask_b32_e64 v28, v28, v29, s[16:17]
	v_cmp_lt_f32_e64 s[40:41], |v174|, s27
	v_cndmask_b32_e32 v29, 0, v157, vcc
	s_nop 0
	v_cndmask_b32_e64 v174, v174, v175, s[40:41]
	v_sub_f32_e32 v28, v28, v29
	v_cndmask_b32_e64 v175, 0, v157, s[36:37]
	v_sub_f32_e32 v28, v0, v28
	v_sub_f32_e32 v174, v174, v175
	v_mul_f32_e32 v29, 0x3d800000, v28
	v_sub_f32_e32 v174, v170, v174
	v_mov_b32_dpp v0, v2 row_shr:1 row_mask:0xf bank_mask:0xf bound_ctrl:1
	v_mul_f32_e32 v175, 0x3d800000, v174
	v_fmac_f32_e32 v0, 0x3d800000, v1
	v_mov_b32_dpp v170, v172 row_shr:1 row_mask:0xf bank_mask:0xf bound_ctrl:1
	v_mov_b32_dpp v1, v29 row_shr:1 row_mask:0xf bank_mask:0xf bound_ctrl:1
	v_fmac_f32_e32 v170, 0x3d800000, v171
	v_fmac_f32_e32 v1, 0x3d800000, v28
	v_mov_b32_dpp v171, v175 row_shr:1 row_mask:0xf bank_mask:0xf bound_ctrl:1
	v_add_f32_dpp v0, v0, v0 row_shr:2 row_mask:0xf bank_mask:0xf bound_ctrl:1
	v_fmac_f32_e32 v171, 0x3d800000, v174
	v_lshlrev_b32_e32 v28, 16, v123
	v_add_f32_dpp v170, v170, v170 row_shr:2 row_mask:0xf bank_mask:0xf bound_ctrl:1
	v_lshlrev_b32_e32 v174, 16, v121
	v_add_f32_dpp v1, v1, v1 row_shr:2 row_mask:0xf bank_mask:0xf bound_ctrl:1
	v_add_f32_dpp v171, v171, v171 row_shr:2 row_mask:0xf bank_mask:0xf bound_ctrl:1
	v_add_f32_dpp v0, v0, v0 row_shr:4 row_mask:0xf bank_mask:0xf bound_ctrl:1
	v_add_f32_dpp v170, v170, v170 row_shr:4 row_mask:0xf bank_mask:0xf bound_ctrl:1
	v_and_b32_e32 v29, 0xffff0000, v123
	v_and_b32_e32 v175, 0xffff0000, v121
	v_add_f32_dpp v1, v1, v1 row_shr:4 row_mask:0xf bank_mask:0xf bound_ctrl:1
	v_add_f32_dpp v171, v171, v171 row_shr:4 row_mask:0xf bank_mask:0xf bound_ctrl:1
	v_add_f32_dpp v2, v0, v0 row_shr:8 row_mask:0xf bank_mask:0xf bound_ctrl:1
	v_add_f32_dpp v172, v170, v170 row_shr:8 row_mask:0xf bank_mask:0xf bound_ctrl:1
	v_mul_f32_e32 v32, 0x3fb8aa3b, v2
	v_mul_f32_e32 v178, 0x3fb8aa3b, v172
	v_add_f32_dpp v125, v1, v1 row_shr:8 row_mask:0xf bank_mask:0xf bound_ctrl:1
	v_add_f32_dpp v182, v171, v171 row_shr:8 row_mask:0xf bank_mask:0xf bound_ctrl:1
	v_mul_f32_e32 v33, 0x3fb8aa3b, v125
	v_mul_f32_e32 v179, 0x3fb8aa3b, v182
	v_exp_f32_e32 v32, v32
	v_exp_f32_e32 v178, v178
	v_exp_f32_e32 v33, v33
	v_exp_f32_e32 v179, v179
	ds_bpermute_b32 v0, v100, v2
	ds_bpermute_b32 v170, v100, v172
	v_mul_f32_e32 v34, 0xbfb8aa3b, v2
	v_mul_f32_e32 v180, 0xbfb8aa3b, v172
	v_mul_f32_e32 v35, 0xbfb8aa3b, v125
	v_mul_f32_e32 v181, 0xbfb8aa3b, v182
	v_exp_f32_e32 v34, v34
	v_exp_f32_e32 v180, v180
	v_exp_f32_e32 v35, v35
	v_exp_f32_e32 v181, v181
	ds_bpermute_b32 v1, v100, v125
	ds_bpermute_b32 v171, v100, v182
	v_pk_mul_f32 v[28:29], v[32:33], v[28:29]
	v_pk_mul_f32 v[174:175], v[178:179], v[174:175]
	s_waitcnt lgkmcnt(3)
	v_sub_f32_e32 v2, v0, v2
	s_waitcnt lgkmcnt(2)
	v_sub_f32_e32 v172, v170, v172
	v_cvt_pk_bf16_f32 v32, v28, v29
	v_cvt_pk_bf16_f32 v178, v174, v175
	v_pk_mul_f32 v[28:29], v[30:31], s[2:3] op_sel_hi:[1,0]
	v_pk_mul_f32 v[174:175], v[176:177], s[38:39] op_sel_hi:[1, 0]
	v_mul_f32_e32 v2, 0x3fb8aa3b, v2
	v_mul_f32_e32 v172, 0x3fb8aa3b, v172
	v_pk_mul_f32 v[30:31], v[28:29], v[34:35]
	v_pk_mul_f32 v[176:177], v[174:175], v[180:181]
	v_exp_f32_e32 v2, v2
	v_exp_f32_e32 v172, v172
	v_cvt_pk_bf16_f32 v30, v30, v31
	v_cvt_pk_bf16_f32 v176, v176, v177
	ds_write2st64_b32 v101, v32, v30 offset1:9
	ds_write2st64_b32 v101, v178, v176 offset0:47 offset1:56
	s_waitcnt lgkmcnt(3)
	v_sub_f32_e32 v30, v1, v125
	s_waitcnt lgkmcnt(2)
	v_sub_f32_e32 v176, v171, v182
	v_mul_f32_e32 v30, 0x3fb8aa3b, v30
	v_mul_f32_e32 v176, 0x3fb8aa3b, v176
	v_exp_f32_e32 v30, v30
	v_exp_f32_e32 v176, v176
	v_mul_f32_e32 v2, v28, v2
	v_mul_f32_e32 v172, v174, v172
	v_cvt_pk_bf16_f32 v2, v2, s0
	v_cvt_pk_bf16_f32 v172, v172, s0
	ds_write_b16 v102, v2 offset:4608
	ds_write_b16 v102, v172 offset:16640
	v_mul_f32_e32 v2, v29, v30
	v_mul_f32_e32 v172, v175, v176
	v_cvt_pk_bf16_f32 v2, v2, s0
	v_cvt_pk_bf16_f32 v172, v172, s0
	ds_write_b16 v102, v2 offset:4640
	ds_write_b16 v102, v172 offset:16672
	s_and_saveexec_b64 s[2:3], s[14:15]
	s_cbranch_execz .LBB0_693
	v_mul_f32_e32 v1, 0x3fb8aa3b, v1
	v_mul_f32_e32 v0, 0x3fb8aa3b, v0
	v_exp_f32_e32 v1, v1
	v_exp_f32_e32 v0, v0
	ds_write_b64 v103, v[0:1] offset:11776
.LBB0_693:
	s_or_b64 exec, exec, s[2:3]
	s_and_saveexec_b64 s[38:39], s[14:15]
	s_cbranch_execz .Lil_t_676
	v_mul_f32_e32 v171, 0x3fb8aa3b, v171
	v_mul_f32_e32 v170, 0x3fb8aa3b, v170
	v_exp_f32_e32 v171, v171
	v_exp_f32_e32 v170, v170
	ds_write_b64 v103, v[170:171] offset:23808
.Lil_t_676:
	s_or_b64 exec, exec, s[38:39]
	s_branch .LBB0_676
